# move last 2 LDS-DMA pieces of each 6-piece load segment into the following MMA block; vmcnt 8->6 there
# baseline (speedup 1.0000x reference)
.LBB0_323:
	ds_read_b128 v[96:99], v209
	ds_read_b128 v[100:103], v209 offset:1024
	ds_read_b128 v[120:123], v209 offset:2048
	ds_read_b128 v[124:127], v209 offset:3072
	ds_read_b128 v[144:147], v210
	ds_read_b128 v[148:151], v210 offset:1024
	ds_read_b128 v[152:155], v210 offset:2048
	ds_read_b128 v[156:159], v210 offset:3072
	s_add_u32 s8, s6, 0xfffc0080
	s_addc_u32 s9, s7, -1
	s_cmp_eq_u32 s78, 12
	s_cselect_b32 s51, s18, s9
	s_cselect_b32 s50, s43, s8
	s_cselect_b32 s9, s45, s57
	s_cselect_b32 s8, s55, s56
	v_lshl_add_u64 v[206:207], s[6:7], 0, v[170:171]
	s_add_i32 m0, s17, 0xc000
	ds_read_b128 v[178:181], v211
	ds_read_b128 v[182:185], v211 offset:1024
	ds_read_b128 v[186:189], v211 offset:2048
	ds_read_b128 v[190:193], v211 offset:3072
	ds_read_b128 v[194:197], v211 offset:4096
	ds_read_b128 v[198:201], v211 offset:5120
	ds_read_b128 v[202:205], v211 offset:6144
	ds_read_b128 v[218:221], v211 offset:7168
	global_load_lds_dwordx4 v[206:207], off
	v_lshl_add_u64 v[206:207], s[6:7], 0, v[172:173]
	s_add_i32 m0, s17, 0xe000
	s_nop 0
	global_load_lds_dwordx4 v[206:207], off
	s_waitcnt vmcnt(8)
	s_waitcnt lgkmcnt(0)
	s_barrier
	s_setprio 1
	s_waitcnt lgkmcnt(0)
	v_mfma_f32_16x16x32_bf16 v[140:143], v[96:99], v[178:181], v[140:143]
	v_mfma_f32_16x16x32_bf16 v[136:139], v[120:123], v[178:181], v[136:139]
	v_mfma_f32_16x16x32_bf16 v[116:119], v[96:99], v[186:189], v[116:119]
	v_mfma_f32_16x16x32_bf16 v[112:115], v[120:123], v[186:189], v[112:115]
	v_mfma_f32_16x16x32_bf16 v[92:95], v[96:99], v[194:197], v[92:95]
	v_mfma_f32_16x16x32_bf16 v[88:91], v[120:123], v[194:197], v[88:91]
	v_mfma_f32_16x16x32_bf16 v[76:79], v[96:99], v[202:205], v[76:79]
	v_mfma_f32_16x16x32_bf16 v[72:75], v[120:123], v[202:205], v[72:75]
	v_mfma_f32_16x16x32_bf16 v[140:143], v[100:103], v[182:185], v[140:143]
	v_mfma_f32_16x16x32_bf16 v[136:139], v[124:127], v[182:185], v[136:139]
	v_mfma_f32_16x16x32_bf16 v[116:119], v[100:103], v[190:193], v[116:119]
	v_mfma_f32_16x16x32_bf16 v[112:115], v[124:127], v[190:193], v[112:115]
	v_mfma_f32_16x16x32_bf16 v[92:95], v[100:103], v[198:201], v[92:95]
	v_mfma_f32_16x16x32_bf16 v[88:91], v[124:127], v[198:201], v[88:91]
	v_mfma_f32_16x16x32_bf16 v[76:79], v[100:103], v[218:221], v[76:79]
	v_mfma_f32_16x16x32_bf16 v[72:75], v[124:127], v[218:221], v[72:75]
	s_setprio 0
	s_setprio 1
	v_mfma_f32_16x16x32_bf16 v[132:135], v[144:147], v[178:181], v[132:135]
	v_mfma_f32_16x16x32_bf16 v[128:131], v[152:155], v[178:181], v[128:131]
	v_mfma_f32_16x16x32_bf16 v[108:111], v[144:147], v[186:189], v[108:111]
	v_mfma_f32_16x16x32_bf16 v[104:107], v[152:155], v[186:189], v[104:107]
	v_mfma_f32_16x16x32_bf16 v[84:87], v[144:147], v[194:197], v[84:87]
	v_mfma_f32_16x16x32_bf16 v[80:83], v[152:155], v[194:197], v[80:83]
	v_mfma_f32_16x16x32_bf16 v[68:71], v[144:147], v[202:205], v[68:71]
	v_mfma_f32_16x16x32_bf16 v[64:67], v[152:155], v[202:205], v[64:67]
	v_mfma_f32_16x16x32_bf16 v[132:135], v[148:151], v[182:185], v[132:135]
	v_mfma_f32_16x16x32_bf16 v[128:131], v[156:159], v[182:185], v[128:131]
	v_mfma_f32_16x16x32_bf16 v[108:111], v[148:151], v[190:193], v[108:111]
	v_mfma_f32_16x16x32_bf16 v[104:107], v[156:159], v[190:193], v[104:107]
	s_setprio 2
	s_barrier
	v_mfma_f32_16x16x32_bf16 v[84:87], v[148:151], v[198:201], v[84:87]
	v_mfma_f32_16x16x32_bf16 v[80:83], v[156:159], v[198:201], v[80:83]
	v_mfma_f32_16x16x32_bf16 v[68:71], v[148:151], v[218:221], v[68:71]
	v_mfma_f32_16x16x32_bf16 v[64:67], v[156:159], v[218:221], v[64:67]
	s_setprio 0
	s_add_i32 s79, s73, s61
	v_lshl_add_u64 v[206:207], s[8:9], 0, v[162:163]
	s_mov_b32 m0, s79
	ds_read_b128 v[178:181], v211 offset:16384
	ds_read_b128 v[182:185], v211 offset:17408
	ds_read_b128 v[186:189], v211 offset:18432
	ds_read_b128 v[190:193], v211 offset:19456
	ds_read_b128 v[194:197], v211 offset:20480
	ds_read_b128 v[198:201], v211 offset:21504
	ds_read_b128 v[202:205], v211 offset:22528
	ds_read_b128 v[218:221], v211 offset:23552
	global_load_lds_dwordx4 v[206:207], off
	s_add_i32 m0, s79, 0x2000
	s_add_u32 s80, s8, 0x40000
	v_lshl_add_u64 v[222:223], s[8:9], 0, v[166:167]
	s_addc_u32 s81, s9, 0
	s_add_i32 s79, s74, s61
	global_load_lds_dwordx4 v[222:223], off
	v_lshl_add_u64 v[224:225], s[80:81], 0, v[162:163]
	s_mov_b32 m0, s79
	v_lshl_add_u64 v[226:227], s[50:51], 0, v[164:165]
	global_load_lds_dwordx4 v[224:225], off
	v_lshl_add_u64 v[224:225], s[80:81], 0, v[166:167]
	s_add_i32 m0, s79, 0x2000
	s_nop 0
	global_load_lds_dwordx4 v[224:225], off
	s_waitcnt vmcnt(6)
	s_waitcnt lgkmcnt(0)
	s_barrier
	s_setprio 1
	s_waitcnt lgkmcnt(0)
	v_mfma_f32_16x16x32_bf16 v[60:63], v[96:99], v[178:181], v[60:63]
	v_mfma_f32_16x16x32_bf16 v[56:59], v[120:123], v[178:181], v[56:59]
	v_lshl_add_u64 v[224:225], s[50:51], 0, v[160:161]
	v_mfma_f32_16x16x32_bf16 v[44:47], v[96:99], v[186:189], v[44:47]
	s_mov_b32 m0, s17
	v_mfma_f32_16x16x32_bf16 v[40:43], v[120:123], v[186:189], v[40:43]
	global_load_lds_dwordx4 v[224:225], off
	v_mfma_f32_16x16x32_bf16 v[28:31], v[96:99], v[194:197], v[28:31]
	s_mov_b32 m0, s62
	v_mfma_f32_16x16x32_bf16 v[24:27], v[120:123], v[194:197], v[24:27]
	global_load_lds_dwordx4 v[226:227], off
	v_mfma_f32_16x16x32_bf16 v[12:15], v[96:99], v[202:205], v[12:15]
	v_mfma_f32_16x16x32_bf16 v[8:11], v[120:123], v[202:205], v[8:11]
	v_mfma_f32_16x16x32_bf16 v[60:63], v[100:103], v[182:185], v[60:63]
	v_mfma_f32_16x16x32_bf16 v[56:59], v[124:127], v[182:185], v[56:59]
	v_mfma_f32_16x16x32_bf16 v[44:47], v[100:103], v[190:193], v[44:47]
	v_mfma_f32_16x16x32_bf16 v[40:43], v[124:127], v[190:193], v[40:43]
	v_mfma_f32_16x16x32_bf16 v[28:31], v[100:103], v[198:201], v[28:31]
	v_mfma_f32_16x16x32_bf16 v[24:27], v[124:127], v[198:201], v[24:27]
	v_mfma_f32_16x16x32_bf16 v[12:15], v[100:103], v[218:221], v[12:15]
	v_mfma_f32_16x16x32_bf16 v[8:11], v[124:127], v[218:221], v[8:11]
	s_setprio 0
	s_setprio 1
	v_mfma_f32_16x16x32_bf16 v[52:55], v[144:147], v[178:181], v[52:55]
	v_mfma_f32_16x16x32_bf16 v[48:51], v[152:155], v[178:181], v[48:51]
	v_mfma_f32_16x16x32_bf16 v[36:39], v[144:147], v[186:189], v[36:39]
	v_mfma_f32_16x16x32_bf16 v[32:35], v[152:155], v[186:189], v[32:35]
	v_mfma_f32_16x16x32_bf16 v[20:23], v[144:147], v[194:197], v[20:23]
	v_mfma_f32_16x16x32_bf16 v[16:19], v[152:155], v[194:197], v[16:19]
	v_mfma_f32_16x16x32_bf16 v[4:7], v[144:147], v[202:205], v[4:7]
	v_mfma_f32_16x16x32_bf16 v[0:3], v[152:155], v[202:205], v[0:3]
	v_mfma_f32_16x16x32_bf16 v[52:55], v[148:151], v[182:185], v[52:55]
	v_mfma_f32_16x16x32_bf16 v[48:51], v[156:159], v[182:185], v[48:51]
	v_mfma_f32_16x16x32_bf16 v[36:39], v[148:151], v[190:193], v[36:39]
	v_mfma_f32_16x16x32_bf16 v[32:35], v[156:159], v[190:193], v[32:35]
	s_setprio 2
	s_barrier
	v_mfma_f32_16x16x32_bf16 v[20:23], v[148:151], v[198:201], v[20:23]
	v_mfma_f32_16x16x32_bf16 v[16:19], v[156:159], v[198:201], v[16:19]
	v_mfma_f32_16x16x32_bf16 v[4:7], v[148:151], v[218:221], v[4:7]
	v_mfma_f32_16x16x32_bf16 v[0:3], v[156:159], v[218:221], v[0:3]
	s_setprio 0
	s_add_i32 s79, 0, 0x18000
	s_add_i32 s80, 0, 0x1c000
	v_add_u32_e32 v124, s79, v208
	v_add_u32_e32 v156, s80, v208
	ds_read_b128 v[96:99], v124
	ds_read_b128 v[100:103], v124 offset:1024
	ds_read_b128 v[120:123], v124 offset:2048
	ds_read_b128 v[124:127], v124 offset:3072
	ds_read_b128 v[144:147], v156
	ds_read_b128 v[148:151], v156 offset:1024
	ds_read_b128 v[152:155], v156 offset:2048
	ds_read_b128 v[156:159], v156 offset:3072
	s_add_u32 s50, s50, 0x40000
	s_addc_u32 s51, s51, 0
	s_mov_b32 m0, s63
	v_lshl_add_u64 v[228:229], s[50:51], 0, v[160:161]
	ds_read_b128 v[178:181], v211 offset:32768
	ds_read_b128 v[182:185], v211 offset:33792
	ds_read_b128 v[186:189], v211 offset:34816
	ds_read_b128 v[190:193], v211 offset:35840
	ds_read_b128 v[194:197], v211 offset:36864
	ds_read_b128 v[198:201], v211 offset:37888
	ds_read_b128 v[202:205], v211 offset:38912
	ds_read_b128 v[218:221], v211 offset:39936
	global_load_lds_dwordx4 v[228:229], off
	v_lshl_add_u64 v[228:229], s[50:51], 0, v[164:165]
	s_mov_b32 m0, s64
	s_nop 0
	global_load_lds_dwordx4 v[228:229], off
	s_waitcnt vmcnt(8)
	s_waitcnt lgkmcnt(0)
	s_barrier
	s_setprio 1
	s_waitcnt lgkmcnt(0)
	v_mfma_f32_16x16x32_bf16 v[140:143], v[96:99], v[178:181], v[140:143]
	v_mfma_f32_16x16x32_bf16 v[136:139], v[120:123], v[178:181], v[136:139]
	v_mfma_f32_16x16x32_bf16 v[116:119], v[96:99], v[186:189], v[116:119]
	v_mfma_f32_16x16x32_bf16 v[112:115], v[120:123], v[186:189], v[112:115]
	v_mfma_f32_16x16x32_bf16 v[92:95], v[96:99], v[194:197], v[92:95]
	v_mfma_f32_16x16x32_bf16 v[88:91], v[120:123], v[194:197], v[88:91]
	v_mfma_f32_16x16x32_bf16 v[76:79], v[96:99], v[202:205], v[76:79]
	v_mfma_f32_16x16x32_bf16 v[72:75], v[120:123], v[202:205], v[72:75]
	v_mfma_f32_16x16x32_bf16 v[140:143], v[100:103], v[182:185], v[140:143]
	v_mfma_f32_16x16x32_bf16 v[136:139], v[124:127], v[182:185], v[136:139]
	v_mfma_f32_16x16x32_bf16 v[116:119], v[100:103], v[190:193], v[116:119]
	v_mfma_f32_16x16x32_bf16 v[112:115], v[124:127], v[190:193], v[112:115]
	v_mfma_f32_16x16x32_bf16 v[92:95], v[100:103], v[198:201], v[92:95]
	v_mfma_f32_16x16x32_bf16 v[88:91], v[124:127], v[198:201], v[88:91]
	v_mfma_f32_16x16x32_bf16 v[76:79], v[100:103], v[218:221], v[76:79]
	v_mfma_f32_16x16x32_bf16 v[72:75], v[124:127], v[218:221], v[72:75]
	s_setprio 0
	s_setprio 1
	v_mfma_f32_16x16x32_bf16 v[132:135], v[144:147], v[178:181], v[132:135]
	v_mfma_f32_16x16x32_bf16 v[128:131], v[152:155], v[178:181], v[128:131]
	v_mfma_f32_16x16x32_bf16 v[108:111], v[144:147], v[186:189], v[108:111]
	v_mfma_f32_16x16x32_bf16 v[104:107], v[152:155], v[186:189], v[104:107]
	v_mfma_f32_16x16x32_bf16 v[84:87], v[144:147], v[194:197], v[84:87]
	v_mfma_f32_16x16x32_bf16 v[80:83], v[152:155], v[194:197], v[80:83]
	v_mfma_f32_16x16x32_bf16 v[68:71], v[144:147], v[202:205], v[68:71]
	v_mfma_f32_16x16x32_bf16 v[64:67], v[152:155], v[202:205], v[64:67]
	v_mfma_f32_16x16x32_bf16 v[132:135], v[148:151], v[182:185], v[132:135]
	v_mfma_f32_16x16x32_bf16 v[128:131], v[156:159], v[182:185], v[128:131]
	v_mfma_f32_16x16x32_bf16 v[108:111], v[148:151], v[190:193], v[108:111]
	v_mfma_f32_16x16x32_bf16 v[104:107], v[156:159], v[190:193], v[104:107]
	s_setprio 2
	s_barrier
	v_mfma_f32_16x16x32_bf16 v[84:87], v[148:151], v[198:201], v[84:87]
	v_mfma_f32_16x16x32_bf16 v[80:83], v[156:159], v[198:201], v[80:83]
	v_mfma_f32_16x16x32_bf16 v[68:71], v[148:151], v[218:221], v[68:71]
	v_mfma_f32_16x16x32_bf16 v[64:67], v[156:159], v[218:221], v[64:67]
	s_setprio 0
	s_add_i32 s50, s79, s61
	v_lshl_add_u64 v[206:207], v[206:207], 0, s[36:37]
	s_mov_b32 m0, s50
	ds_read_b128 v[178:181], v211 offset:49152
	ds_read_b128 v[182:185], v211 offset:50176
	ds_read_b128 v[186:189], v211 offset:51200
	ds_read_b128 v[190:193], v211 offset:52224
	ds_read_b128 v[194:197], v211 offset:53248
	ds_read_b128 v[198:201], v211 offset:54272
	ds_read_b128 v[202:205], v211 offset:55296
	ds_read_b128 v[218:221], v211 offset:56320
	global_load_lds_dwordx4 v[206:207], off
	s_add_i32 m0, s50, 0x2000
	s_add_u32 s8, s8, 0x40080
	v_lshl_add_u64 v[206:207], v[222:223], 0, s[36:37]
	s_addc_u32 s9, s9, 0
	s_add_i32 s50, s80, s61
	global_load_lds_dwordx4 v[206:207], off
	v_lshl_add_u64 v[206:207], s[8:9], 0, v[162:163]
	s_mov_b32 m0, s50
	s_nop 0
	global_load_lds_dwordx4 v[206:207], off
	v_lshl_add_u64 v[206:207], s[8:9], 0, v[166:167]
	s_add_i32 m0, s50, 0x2000
	s_nop 0
	global_load_lds_dwordx4 v[206:207], off
	s_waitcnt vmcnt(6)
	s_waitcnt lgkmcnt(0)
	s_barrier
	s_setprio 1
	s_waitcnt lgkmcnt(0)
	v_mfma_f32_16x16x32_bf16 v[60:63], v[96:99], v[178:181], v[60:63]
	v_mfma_f32_16x16x32_bf16 v[56:59], v[120:123], v[178:181], v[56:59]
	v_lshl_add_u64 v[206:207], v[224:225], 0, s[36:37]
	v_mfma_f32_16x16x32_bf16 v[44:47], v[96:99], v[186:189], v[44:47]
	s_mov_b32 m0, s68
	v_mfma_f32_16x16x32_bf16 v[40:43], v[120:123], v[186:189], v[40:43]
	global_load_lds_dwordx4 v[206:207], off
	v_mfma_f32_16x16x32_bf16 v[28:31], v[96:99], v[194:197], v[28:31]
	v_lshl_add_u64 v[206:207], v[226:227], 0, s[36:37]
	v_mfma_f32_16x16x32_bf16 v[24:27], v[120:123], v[194:197], v[24:27]
	s_mov_b32 m0, s69
	v_mfma_f32_16x16x32_bf16 v[12:15], v[96:99], v[202:205], v[12:15]
	global_load_lds_dwordx4 v[206:207], off
	v_mfma_f32_16x16x32_bf16 v[8:11], v[120:123], v[202:205], v[8:11]
	v_mfma_f32_16x16x32_bf16 v[60:63], v[100:103], v[182:185], v[60:63]
	v_mfma_f32_16x16x32_bf16 v[56:59], v[124:127], v[182:185], v[56:59]
	v_mfma_f32_16x16x32_bf16 v[44:47], v[100:103], v[190:193], v[44:47]
	v_mfma_f32_16x16x32_bf16 v[40:43], v[124:127], v[190:193], v[40:43]
	v_mfma_f32_16x16x32_bf16 v[28:31], v[100:103], v[198:201], v[28:31]
	v_mfma_f32_16x16x32_bf16 v[24:27], v[124:127], v[198:201], v[24:27]
	v_mfma_f32_16x16x32_bf16 v[12:15], v[100:103], v[218:221], v[12:15]
	v_mfma_f32_16x16x32_bf16 v[8:11], v[124:127], v[218:221], v[8:11]
	s_setprio 0
	s_setprio 1
	v_mfma_f32_16x16x32_bf16 v[52:55], v[144:147], v[178:181], v[52:55]
	v_mfma_f32_16x16x32_bf16 v[48:51], v[152:155], v[178:181], v[48:51]
	v_mfma_f32_16x16x32_bf16 v[36:39], v[144:147], v[186:189], v[36:39]
	v_mfma_f32_16x16x32_bf16 v[32:35], v[152:155], v[186:189], v[32:35]
	v_mfma_f32_16x16x32_bf16 v[20:23], v[144:147], v[194:197], v[20:23]
	v_mfma_f32_16x16x32_bf16 v[16:19], v[152:155], v[194:197], v[16:19]
	v_mfma_f32_16x16x32_bf16 v[4:7], v[144:147], v[202:205], v[4:7]
	v_mfma_f32_16x16x32_bf16 v[0:3], v[152:155], v[202:205], v[0:3]
	v_mfma_f32_16x16x32_bf16 v[52:55], v[148:151], v[182:185], v[52:55]
	v_mfma_f32_16x16x32_bf16 v[48:51], v[156:159], v[182:185], v[48:51]
	v_mfma_f32_16x16x32_bf16 v[36:39], v[148:151], v[190:193], v[36:39]
	v_mfma_f32_16x16x32_bf16 v[32:35], v[156:159], v[190:193], v[32:35]
	s_setprio 2
	s_barrier
	v_mfma_f32_16x16x32_bf16 v[20:23], v[148:151], v[198:201], v[20:23]
	v_mfma_f32_16x16x32_bf16 v[16:19], v[156:159], v[198:201], v[16:19]
	v_mfma_f32_16x16x32_bf16 v[4:7], v[148:151], v[218:221], v[4:7]
	v_mfma_f32_16x16x32_bf16 v[0:3], v[156:159], v[218:221], v[0:3]
	s_setprio 0
	s_add_i32 s78, s78, 2
	s_add_u32 s6, s6, 0x100
	s_addc_u32 s7, s7, 0
	s_add_u32 s56, s56, 0x100
	s_addc_u32 s57, s57, 0
	s_cmp_gt_u32 s78, 13
	s_cbranch_scc0 .LBB0_323
	s_and_b64 vcc, exec, s[38:39]
	s_cbranch_vccz .LBB0_326
	s_barrier

.LBB0_700:
	ds_read_b128 v[130:133], v203
	ds_read_b128 v[134:137], v203 offset:1024
	ds_read_b128 v[138:141], v203 offset:2048
	ds_read_b128 v[142:145], v203 offset:3072
	ds_read_b128 v[146:149], v195
	ds_read_b128 v[150:153], v195 offset:1024
	ds_read_b128 v[154:157], v195 offset:2048
	ds_read_b128 v[158:161], v195 offset:3072
	s_add_u32 s47, s44, 0xfff80080
	s_addc_u32 s48, s45, -1
	s_cmp_eq_u32 s46, 28
	s_cselect_b32 s49, s29, s48
	s_cselect_b32 s48, s71, s47
	s_cselect_b32 s47, s31, s84
	s_cselect_b32 s46, s72, s83
	s_mov_b32 m0, s73
	v_lshl_add_u64 v[174:175], s[44:45], 0, v[180:181]
	ds_read_b128 v[162:165], v211
	ds_read_b128 v[166:169], v211 offset:1024
	ds_read_b128 v[170:173], v211 offset:2048
	ds_read_b128 v[184:187], v211 offset:3072
	ds_read_b128 v[190:193], v211 offset:4096
	ds_read_b128 v[196:199], v211 offset:5120
	ds_read_b128 v[204:207], v211 offset:6144
	ds_read_b128 v[212:215], v211 offset:7168
	global_load_lds_dwordx4 v[174:175], off
	v_lshl_add_u64 v[174:175], s[44:45], 0, v[182:183]
	s_mov_b32 m0, s74
	s_nop 0
	global_load_lds_dwordx4 v[174:175], off
	s_waitcnt vmcnt(8)
	s_waitcnt lgkmcnt(0)
	s_barrier
	s_setprio 1
	s_waitcnt lgkmcnt(0)
	v_mfma_f32_16x16x32_bf16 v[124:127], v[130:133], v[162:165], v[124:127]
	v_mfma_f32_16x16x32_bf16 v[120:123], v[138:141], v[162:165], v[120:123]
	v_mfma_f32_16x16x32_bf16 v[108:111], v[130:133], v[170:173], v[108:111]
	v_mfma_f32_16x16x32_bf16 v[104:107], v[138:141], v[170:173], v[104:107]
	v_mfma_f32_16x16x32_bf16 v[92:95], v[130:133], v[190:193], v[92:95]
	v_mfma_f32_16x16x32_bf16 v[88:91], v[138:141], v[190:193], v[88:91]
	v_mfma_f32_16x16x32_bf16 v[76:79], v[130:133], v[204:207], v[76:79]
	v_mfma_f32_16x16x32_bf16 v[72:75], v[138:141], v[204:207], v[72:75]
	v_mfma_f32_16x16x32_bf16 v[124:127], v[134:137], v[166:169], v[124:127]
	v_mfma_f32_16x16x32_bf16 v[120:123], v[142:145], v[166:169], v[120:123]
	v_mfma_f32_16x16x32_bf16 v[108:111], v[134:137], v[184:187], v[108:111]
	v_mfma_f32_16x16x32_bf16 v[104:107], v[142:145], v[184:187], v[104:107]
	v_mfma_f32_16x16x32_bf16 v[92:95], v[134:137], v[196:199], v[92:95]
	v_mfma_f32_16x16x32_bf16 v[88:91], v[142:145], v[196:199], v[88:91]
	v_mfma_f32_16x16x32_bf16 v[76:79], v[134:137], v[212:215], v[76:79]
	v_mfma_f32_16x16x32_bf16 v[72:75], v[142:145], v[212:215], v[72:75]
	s_setprio 0
	s_setprio 1
	v_mfma_f32_16x16x32_bf16 v[116:119], v[146:149], v[162:165], v[116:119]
	v_mfma_f32_16x16x32_bf16 v[112:115], v[154:157], v[162:165], v[112:115]
	v_mfma_f32_16x16x32_bf16 v[100:103], v[146:149], v[170:173], v[100:103]
	v_mfma_f32_16x16x32_bf16 v[96:99], v[154:157], v[170:173], v[96:99]
	v_mfma_f32_16x16x32_bf16 v[84:87], v[146:149], v[190:193], v[84:87]
	v_mfma_f32_16x16x32_bf16 v[80:83], v[154:157], v[190:193], v[80:83]
	v_mfma_f32_16x16x32_bf16 v[68:71], v[146:149], v[204:207], v[68:71]
	v_mfma_f32_16x16x32_bf16 v[64:67], v[154:157], v[204:207], v[64:67]
	v_mfma_f32_16x16x32_bf16 v[116:119], v[150:153], v[166:169], v[116:119]
	v_mfma_f32_16x16x32_bf16 v[112:115], v[158:161], v[166:169], v[112:115]
	v_mfma_f32_16x16x32_bf16 v[100:103], v[150:153], v[184:187], v[100:103]
	v_mfma_f32_16x16x32_bf16 v[96:99], v[158:161], v[184:187], v[96:99]
	s_setprio 2
	s_barrier
	v_mfma_f32_16x16x32_bf16 v[84:87], v[150:153], v[196:199], v[84:87]
	v_mfma_f32_16x16x32_bf16 v[80:83], v[158:161], v[196:199], v[80:83]
	v_mfma_f32_16x16x32_bf16 v[68:71], v[150:153], v[212:215], v[68:71]
	v_mfma_f32_16x16x32_bf16 v[64:67], v[158:161], v[212:215], v[64:67]
	s_setprio 0
	s_mov_b32 m0, s75
	v_lshl_add_u64 v[174:175], s[46:47], 0, v[176:177]
	s_add_u32 s86, s46, 0x80000
	ds_read_b128 v[162:165], v211 offset:16384
	ds_read_b128 v[166:169], v211 offset:17408
	ds_read_b128 v[170:173], v211 offset:18432
	ds_read_b128 v[184:187], v211 offset:19456
	ds_read_b128 v[190:193], v211 offset:20480
	ds_read_b128 v[196:199], v211 offset:21504
	ds_read_b128 v[204:207], v211 offset:22528
	ds_read_b128 v[212:215], v211 offset:23552
	global_load_lds_dwordx4 v[174:175], off
	v_lshl_add_u64 v[200:201], s[46:47], 0, v[178:179]
	s_mov_b32 m0, s76
	s_addc_u32 s87, s47, 0
	global_load_lds_dwordx4 v[200:201], off
	v_lshl_add_u64 v[208:209], s[86:87], 0, v[176:177]
	s_mov_b32 m0, s77
	v_lshl_add_u64 v[216:217], s[48:49], 0, v[178:179]
	global_load_lds_dwordx4 v[208:209], off
	v_lshl_add_u64 v[208:209], s[86:87], 0, v[178:179]
	s_mov_b32 m0, s78
	s_nop 0
	global_load_lds_dwordx4 v[208:209], off
	s_waitcnt vmcnt(6)
	s_waitcnt lgkmcnt(0)
	s_barrier
	s_setprio 1
	s_waitcnt lgkmcnt(0)
	v_mfma_f32_16x16x32_bf16 v[60:63], v[130:133], v[162:165], v[60:63]
	v_mfma_f32_16x16x32_bf16 v[56:59], v[138:141], v[162:165], v[56:59]
	v_lshl_add_u64 v[208:209], s[48:49], 0, v[176:177]
	v_mfma_f32_16x16x32_bf16 v[44:47], v[130:133], v[170:173], v[44:47]
	s_mov_b32 m0, s56
	v_mfma_f32_16x16x32_bf16 v[40:43], v[138:141], v[170:173], v[40:43]
	global_load_lds_dwordx4 v[208:209], off
	v_mfma_f32_16x16x32_bf16 v[28:31], v[130:133], v[190:193], v[28:31]
	s_mov_b32 m0, s57
	v_mfma_f32_16x16x32_bf16 v[24:27], v[138:141], v[190:193], v[24:27]
	global_load_lds_dwordx4 v[216:217], off
	v_mfma_f32_16x16x32_bf16 v[12:15], v[130:133], v[204:207], v[12:15]
	v_mfma_f32_16x16x32_bf16 v[8:11], v[138:141], v[204:207], v[8:11]
	v_mfma_f32_16x16x32_bf16 v[60:63], v[134:137], v[166:169], v[60:63]
	v_mfma_f32_16x16x32_bf16 v[56:59], v[142:145], v[166:169], v[56:59]
	v_mfma_f32_16x16x32_bf16 v[44:47], v[134:137], v[184:187], v[44:47]
	v_mfma_f32_16x16x32_bf16 v[40:43], v[142:145], v[184:187], v[40:43]
	v_mfma_f32_16x16x32_bf16 v[28:31], v[134:137], v[196:199], v[28:31]
	v_mfma_f32_16x16x32_bf16 v[24:27], v[142:145], v[196:199], v[24:27]
	v_mfma_f32_16x16x32_bf16 v[12:15], v[134:137], v[212:215], v[12:15]
	v_mfma_f32_16x16x32_bf16 v[8:11], v[142:145], v[212:215], v[8:11]
	s_setprio 0
	s_setprio 1
	v_mfma_f32_16x16x32_bf16 v[52:55], v[146:149], v[162:165], v[52:55]
	v_mfma_f32_16x16x32_bf16 v[48:51], v[154:157], v[162:165], v[48:51]
	v_mfma_f32_16x16x32_bf16 v[36:39], v[146:149], v[170:173], v[36:39]
	v_mfma_f32_16x16x32_bf16 v[32:35], v[154:157], v[170:173], v[32:35]
	v_mfma_f32_16x16x32_bf16 v[20:23], v[146:149], v[190:193], v[20:23]
	v_mfma_f32_16x16x32_bf16 v[16:19], v[154:157], v[190:193], v[16:19]
	v_mfma_f32_16x16x32_bf16 v[4:7], v[146:149], v[204:207], v[4:7]
	v_mfma_f32_16x16x32_bf16 v[0:3], v[154:157], v[204:207], v[0:3]
	v_mfma_f32_16x16x32_bf16 v[52:55], v[150:153], v[166:169], v[52:55]
	v_mfma_f32_16x16x32_bf16 v[48:51], v[158:161], v[166:169], v[48:51]
	v_mfma_f32_16x16x32_bf16 v[36:39], v[150:153], v[184:187], v[36:39]
	v_mfma_f32_16x16x32_bf16 v[32:35], v[158:161], v[184:187], v[32:35]
	s_setprio 2
	s_barrier
	v_mfma_f32_16x16x32_bf16 v[20:23], v[150:153], v[196:199], v[20:23]
	v_mfma_f32_16x16x32_bf16 v[16:19], v[158:161], v[196:199], v[16:19]
	v_mfma_f32_16x16x32_bf16 v[4:7], v[150:153], v[212:215], v[4:7]
	v_mfma_f32_16x16x32_bf16 v[0:3], v[158:161], v[212:215], v[0:3]
	s_setprio 0
	ds_read_b128 v[130:133], v128
	ds_read_b128 v[134:137], v128 offset:1024
	ds_read_b128 v[138:141], v128 offset:2048
	ds_read_b128 v[142:145], v128 offset:3072
	ds_read_b128 v[146:149], v129
	ds_read_b128 v[150:153], v129 offset:1024
	ds_read_b128 v[154:157], v129 offset:2048
	ds_read_b128 v[158:161], v129 offset:3072
	s_add_u32 s48, s48, 0x80000
	s_addc_u32 s49, s49, 0
	s_mov_b32 m0, s58
	v_lshl_add_u64 v[218:219], s[48:49], 0, v[176:177]
	ds_read_b128 v[162:165], v211 offset:32768
	ds_read_b128 v[166:169], v211 offset:33792
	ds_read_b128 v[170:173], v211 offset:34816
	ds_read_b128 v[184:187], v211 offset:35840
	ds_read_b128 v[190:193], v211 offset:36864
	ds_read_b128 v[196:199], v211 offset:37888
	ds_read_b128 v[204:207], v211 offset:38912
	ds_read_b128 v[212:215], v211 offset:39936
	global_load_lds_dwordx4 v[218:219], off
	v_lshl_add_u64 v[218:219], s[48:49], 0, v[178:179]
	s_mov_b32 m0, s59
	s_nop 0
	global_load_lds_dwordx4 v[218:219], off
	s_waitcnt vmcnt(8)
	s_waitcnt lgkmcnt(0)
	s_barrier
	s_setprio 1
	s_waitcnt lgkmcnt(0)
	v_mfma_f32_16x16x32_bf16 v[124:127], v[130:133], v[162:165], v[124:127]
	v_mfma_f32_16x16x32_bf16 v[120:123], v[138:141], v[162:165], v[120:123]
	v_mfma_f32_16x16x32_bf16 v[108:111], v[130:133], v[170:173], v[108:111]
	v_mfma_f32_16x16x32_bf16 v[104:107], v[138:141], v[170:173], v[104:107]
	v_mfma_f32_16x16x32_bf16 v[92:95], v[130:133], v[190:193], v[92:95]
	v_mfma_f32_16x16x32_bf16 v[88:91], v[138:141], v[190:193], v[88:91]
	v_mfma_f32_16x16x32_bf16 v[76:79], v[130:133], v[204:207], v[76:79]
	v_mfma_f32_16x16x32_bf16 v[72:75], v[138:141], v[204:207], v[72:75]
	v_mfma_f32_16x16x32_bf16 v[124:127], v[134:137], v[166:169], v[124:127]
	v_mfma_f32_16x16x32_bf16 v[120:123], v[142:145], v[166:169], v[120:123]
	v_mfma_f32_16x16x32_bf16 v[108:111], v[134:137], v[184:187], v[108:111]
	v_mfma_f32_16x16x32_bf16 v[104:107], v[142:145], v[184:187], v[104:107]
	v_mfma_f32_16x16x32_bf16 v[92:95], v[134:137], v[196:199], v[92:95]
	v_mfma_f32_16x16x32_bf16 v[88:91], v[142:145], v[196:199], v[88:91]
	v_mfma_f32_16x16x32_bf16 v[76:79], v[134:137], v[212:215], v[76:79]
	v_mfma_f32_16x16x32_bf16 v[72:75], v[142:145], v[212:215], v[72:75]
	s_setprio 0
	s_setprio 1
	v_mfma_f32_16x16x32_bf16 v[116:119], v[146:149], v[162:165], v[116:119]
	v_mfma_f32_16x16x32_bf16 v[112:115], v[154:157], v[162:165], v[112:115]
	v_mfma_f32_16x16x32_bf16 v[100:103], v[146:149], v[170:173], v[100:103]
	v_mfma_f32_16x16x32_bf16 v[96:99], v[154:157], v[170:173], v[96:99]
	v_mfma_f32_16x16x32_bf16 v[84:87], v[146:149], v[190:193], v[84:87]
	v_mfma_f32_16x16x32_bf16 v[80:83], v[154:157], v[190:193], v[80:83]
	v_mfma_f32_16x16x32_bf16 v[68:71], v[146:149], v[204:207], v[68:71]
	v_mfma_f32_16x16x32_bf16 v[64:67], v[154:157], v[204:207], v[64:67]
	v_mfma_f32_16x16x32_bf16 v[116:119], v[150:153], v[166:169], v[116:119]
	v_mfma_f32_16x16x32_bf16 v[112:115], v[158:161], v[166:169], v[112:115]
	v_mfma_f32_16x16x32_bf16 v[100:103], v[150:153], v[184:187], v[100:103]
	v_mfma_f32_16x16x32_bf16 v[96:99], v[158:161], v[184:187], v[96:99]
	s_setprio 2
	s_barrier
	v_mfma_f32_16x16x32_bf16 v[84:87], v[150:153], v[196:199], v[84:87]
	v_mfma_f32_16x16x32_bf16 v[80:83], v[158:161], v[196:199], v[80:83]
	v_mfma_f32_16x16x32_bf16 v[68:71], v[150:153], v[212:215], v[68:71]
	v_mfma_f32_16x16x32_bf16 v[64:67], v[158:161], v[212:215], v[64:67]
	s_setprio 0
	s_mov_b32 m0, s79
	v_lshl_add_u64 v[174:175], v[174:175], 0, s[20:21]
	s_add_u32 s46, s46, 0x80080
	ds_read_b128 v[162:165], v211 offset:49152
	ds_read_b128 v[166:169], v211 offset:50176
	ds_read_b128 v[170:173], v211 offset:51200
	ds_read_b128 v[184:187], v211 offset:52224
	ds_read_b128 v[190:193], v211 offset:53248
	ds_read_b128 v[196:199], v211 offset:54272
	ds_read_b128 v[204:207], v211 offset:55296
	ds_read_b128 v[212:215], v211 offset:56320
	global_load_lds_dwordx4 v[174:175], off
	v_lshl_add_u64 v[174:175], v[200:201], 0, s[20:21]
	s_mov_b32 m0, s80
	s_addc_u32 s47, s47, 0
	global_load_lds_dwordx4 v[174:175], off
	v_lshl_add_u64 v[174:175], s[46:47], 0, v[176:177]
	s_mov_b32 m0, s81
	s_nop 0
	global_load_lds_dwordx4 v[174:175], off
	v_lshl_add_u64 v[174:175], s[46:47], 0, v[178:179]
	s_mov_b32 m0, s82
	s_nop 0
	global_load_lds_dwordx4 v[174:175], off
	s_waitcnt vmcnt(6)
	s_waitcnt lgkmcnt(0)
	s_barrier
	s_setprio 1
	s_waitcnt lgkmcnt(0)
	v_mfma_f32_16x16x32_bf16 v[60:63], v[130:133], v[162:165], v[60:63]
	v_mfma_f32_16x16x32_bf16 v[56:59], v[138:141], v[162:165], v[56:59]
	v_lshl_add_u64 v[174:175], v[208:209], 0, s[20:21]
	v_mfma_f32_16x16x32_bf16 v[44:47], v[130:133], v[170:173], v[44:47]
	s_mov_b32 m0, s61
	v_mfma_f32_16x16x32_bf16 v[40:43], v[138:141], v[170:173], v[40:43]
	global_load_lds_dwordx4 v[174:175], off
	v_mfma_f32_16x16x32_bf16 v[28:31], v[130:133], v[190:193], v[28:31]
	v_lshl_add_u64 v[174:175], v[216:217], 0, s[20:21]
	v_mfma_f32_16x16x32_bf16 v[24:27], v[138:141], v[190:193], v[24:27]
	s_mov_b32 m0, s62
	v_mfma_f32_16x16x32_bf16 v[12:15], v[130:133], v[204:207], v[12:15]
	global_load_lds_dwordx4 v[174:175], off
	v_mfma_f32_16x16x32_bf16 v[8:11], v[138:141], v[204:207], v[8:11]
	v_mfma_f32_16x16x32_bf16 v[60:63], v[134:137], v[166:169], v[60:63]
	v_mfma_f32_16x16x32_bf16 v[56:59], v[142:145], v[166:169], v[56:59]
	v_mfma_f32_16x16x32_bf16 v[44:47], v[134:137], v[184:187], v[44:47]
	v_mfma_f32_16x16x32_bf16 v[40:43], v[142:145], v[184:187], v[40:43]
	v_mfma_f32_16x16x32_bf16 v[28:31], v[134:137], v[196:199], v[28:31]
	v_mfma_f32_16x16x32_bf16 v[24:27], v[142:145], v[196:199], v[24:27]
	v_mfma_f32_16x16x32_bf16 v[12:15], v[134:137], v[212:215], v[12:15]
	v_mfma_f32_16x16x32_bf16 v[8:11], v[142:145], v[212:215], v[8:11]
	s_setprio 0
	s_setprio 1
	v_mfma_f32_16x16x32_bf16 v[52:55], v[146:149], v[162:165], v[52:55]
	v_mfma_f32_16x16x32_bf16 v[48:51], v[154:157], v[162:165], v[48:51]
	v_mfma_f32_16x16x32_bf16 v[36:39], v[146:149], v[170:173], v[36:39]
	v_mfma_f32_16x16x32_bf16 v[32:35], v[154:157], v[170:173], v[32:35]
	v_mfma_f32_16x16x32_bf16 v[20:23], v[146:149], v[190:193], v[20:23]
	v_mfma_f32_16x16x32_bf16 v[16:19], v[154:157], v[190:193], v[16:19]
	v_mfma_f32_16x16x32_bf16 v[4:7], v[146:149], v[204:207], v[4:7]
	v_mfma_f32_16x16x32_bf16 v[0:3], v[154:157], v[204:207], v[0:3]
	v_mfma_f32_16x16x32_bf16 v[52:55], v[150:153], v[166:169], v[52:55]
	v_mfma_f32_16x16x32_bf16 v[48:51], v[158:161], v[166:169], v[48:51]
	v_mfma_f32_16x16x32_bf16 v[36:39], v[150:153], v[184:187], v[36:39]
	v_mfma_f32_16x16x32_bf16 v[32:35], v[158:161], v[184:187], v[32:35]
	s_setprio 2
	s_barrier
	v_mfma_f32_16x16x32_bf16 v[20:23], v[150:153], v[196:199], v[20:23]
	v_mfma_f32_16x16x32_bf16 v[16:19], v[158:161], v[196:199], v[16:19]
	v_mfma_f32_16x16x32_bf16 v[4:7], v[150:153], v[212:215], v[4:7]
	v_mfma_f32_16x16x32_bf16 v[0:3], v[158:161], v[212:215], v[0:3]
	s_setprio 0
	s_add_i32 s70, s70, 1
	s_add_u32 s44, s44, 0x100
	s_addc_u32 s45, s45, 0
	s_add_u32 s83, s83, 0x100
	s_addc_u32 s84, s84, 0
	s_cmp_gt_u32 s85, 29
	s_cbranch_scc0 .LBB0_698
	s_lshl_b32 s29, s41, 12
	s_and_b32 s29, s29, 0x1000
	s_add_i32 s29, s29, 0
	v_mbcnt_lo_u32_b32 v128, -1, 0
	v_mbcnt_hi_u32_b32 v128, -1, v128
	s_add_i32 s29, s29, s63
	v_lshlrev_b32_e32 v128, 4, v128
	s_add_i32 s29, s29, 0x20400
	v_and_b32_e32 v128, 0xf0, v128
	v_add_u32_e32 v128, s29, v128
	ds_read2_b32 v[214:215], v128 offset0:3 offset1:67
	ds_read2_b32 v[206:207], v128 offset0:131 offset1:195
	v_add_u32_e32 v128, 12, v128
	ds_read2st64_b32 v[196:197], v128 offset0:8 offset1:9
	ds_read2st64_b32 v[190:191], v128 offset0:10 offset1:11
	s_and_b64 vcc, exec, s[22:23]
	s_waitcnt lgkmcnt(0)
	v_mov_b32_e32 v210, v215
	v_mov_b32_e32 v202, v207
	v_mov_b32_e32 v194, v197
	v_mov_b32_e32 v188, v191
	s_cbranch_vccz .LBB0_703
	s_barrier

.LBB0_784:
	ds_read_b128 v[144:147], v163
	ds_read_b128 v[148:151], v163 offset:1024
	ds_read_b128 v[152:155], v163 offset:2048
	ds_read_b128 v[156:159], v163 offset:3072
	ds_read_b128 v[168:171], v164
	ds_read_b128 v[172:175], v164 offset:1024
	ds_read_b128 v[176:179], v164 offset:2048
	ds_read_b128 v[180:183], v164 offset:3072
	s_add_u32 s38, s36, 0xfffc0080
	s_addc_u32 s39, s37, -1
	s_cmp_eq_u32 s65, 12
	s_cselect_b32 s41, s23, s39
	s_cselect_b32 s40, s31, s38
	s_cselect_b32 s39, s25, s64
	s_cselect_b32 s38, s62, s63
	v_lshl_add_u64 v[160:161], s[36:37], 0, v[136:137]
	s_add_i32 m0, s50, 0xc000
	ds_read_b128 v[184:187], v165
	ds_read_b128 v[188:191], v165 offset:1024
	ds_read_b128 v[192:195], v165 offset:2048
	ds_read_b128 v[196:199], v165 offset:3072
	ds_read_b128 v[200:203], v165 offset:4096
	ds_read_b128 v[204:207], v165 offset:5120
	ds_read_b128 v[208:211], v165 offset:6144
	ds_read_b128 v[212:215], v165 offset:7168
	global_load_lds_dwordx4 v[160:161], off
	v_lshl_add_u64 v[160:161], s[36:37], 0, v[138:139]
	s_add_i32 m0, s50, 0xe000
	s_nop 0
	global_load_lds_dwordx4 v[160:161], off
	s_waitcnt vmcnt(8)
	s_waitcnt lgkmcnt(0)
	s_barrier
	s_setprio 1
	s_waitcnt lgkmcnt(0)
	v_mfma_f32_16x16x32_bf16 v[124:127], v[144:147], v[184:187], v[124:127]
	v_mfma_f32_16x16x32_bf16 v[120:123], v[152:155], v[184:187], v[120:123]
	v_mfma_f32_16x16x32_bf16 v[108:111], v[144:147], v[192:195], v[108:111]
	v_mfma_f32_16x16x32_bf16 v[104:107], v[152:155], v[192:195], v[104:107]
	v_mfma_f32_16x16x32_bf16 v[92:95], v[144:147], v[200:203], v[92:95]
	v_mfma_f32_16x16x32_bf16 v[88:91], v[152:155], v[200:203], v[88:91]
	v_mfma_f32_16x16x32_bf16 v[76:79], v[144:147], v[208:211], v[76:79]
	v_mfma_f32_16x16x32_bf16 v[72:75], v[152:155], v[208:211], v[72:75]
	v_mfma_f32_16x16x32_bf16 v[124:127], v[148:151], v[188:191], v[124:127]
	v_mfma_f32_16x16x32_bf16 v[120:123], v[156:159], v[188:191], v[120:123]
	v_mfma_f32_16x16x32_bf16 v[108:111], v[148:151], v[196:199], v[108:111]
	v_mfma_f32_16x16x32_bf16 v[104:107], v[156:159], v[196:199], v[104:107]
	v_mfma_f32_16x16x32_bf16 v[92:95], v[148:151], v[204:207], v[92:95]
	v_mfma_f32_16x16x32_bf16 v[88:91], v[156:159], v[204:207], v[88:91]
	v_mfma_f32_16x16x32_bf16 v[76:79], v[148:151], v[212:215], v[76:79]
	v_mfma_f32_16x16x32_bf16 v[72:75], v[156:159], v[212:215], v[72:75]
	s_setprio 0
	s_setprio 1
	v_mfma_f32_16x16x32_bf16 v[116:119], v[168:171], v[184:187], v[116:119]
	v_mfma_f32_16x16x32_bf16 v[112:115], v[176:179], v[184:187], v[112:115]
	v_mfma_f32_16x16x32_bf16 v[100:103], v[168:171], v[192:195], v[100:103]
	v_mfma_f32_16x16x32_bf16 v[96:99], v[176:179], v[192:195], v[96:99]
	v_mfma_f32_16x16x32_bf16 v[84:87], v[168:171], v[200:203], v[84:87]
	v_mfma_f32_16x16x32_bf16 v[80:83], v[176:179], v[200:203], v[80:83]
	v_mfma_f32_16x16x32_bf16 v[68:71], v[168:171], v[208:211], v[68:71]
	v_mfma_f32_16x16x32_bf16 v[64:67], v[176:179], v[208:211], v[64:67]
	v_mfma_f32_16x16x32_bf16 v[116:119], v[172:175], v[188:191], v[116:119]
	v_mfma_f32_16x16x32_bf16 v[112:115], v[180:183], v[188:191], v[112:115]
	v_mfma_f32_16x16x32_bf16 v[100:103], v[172:175], v[196:199], v[100:103]
	v_mfma_f32_16x16x32_bf16 v[96:99], v[180:183], v[196:199], v[96:99]
	s_setprio 2
	s_barrier
	v_mfma_f32_16x16x32_bf16 v[84:87], v[172:175], v[204:207], v[84:87]
	v_mfma_f32_16x16x32_bf16 v[80:83], v[180:183], v[204:207], v[80:83]
	v_mfma_f32_16x16x32_bf16 v[68:71], v[172:175], v[212:215], v[68:71]
	v_mfma_f32_16x16x32_bf16 v[64:67], v[180:183], v[212:215], v[64:67]
	s_setprio 0
	s_add_i32 s66, s59, s47
	v_lshl_add_u64 v[160:161], s[38:39], 0, v[132:133]
	s_mov_b32 m0, s66
	ds_read_b128 v[184:187], v165 offset:16384
	ds_read_b128 v[188:191], v165 offset:17408
	ds_read_b128 v[192:195], v165 offset:18432
	ds_read_b128 v[196:199], v165 offset:19456
	ds_read_b128 v[200:203], v165 offset:20480
	ds_read_b128 v[204:207], v165 offset:21504
	ds_read_b128 v[208:211], v165 offset:22528
	ds_read_b128 v[212:215], v165 offset:23552
	global_load_lds_dwordx4 v[160:161], off
	s_add_i32 m0, s66, 0x2000
	s_add_u32 s66, s38, 0x40000
	v_lshl_add_u64 v[216:217], s[38:39], 0, v[128:129]
	s_addc_u32 s67, s39, 0
	s_add_i32 s68, s60, s47
	global_load_lds_dwordx4 v[216:217], off
	v_lshl_add_u64 v[218:219], s[66:67], 0, v[132:133]
	s_mov_b32 m0, s68
	v_lshl_add_u64 v[220:221], s[40:41], 0, v[130:131]
	global_load_lds_dwordx4 v[218:219], off
	v_lshl_add_u64 v[218:219], s[66:67], 0, v[128:129]
	s_add_i32 m0, s68, 0x2000
	s_nop 0
	global_load_lds_dwordx4 v[218:219], off
	s_waitcnt vmcnt(6)
	s_waitcnt lgkmcnt(0)
	s_barrier
	s_setprio 1
	s_waitcnt lgkmcnt(0)
	v_mfma_f32_16x16x32_bf16 v[60:63], v[144:147], v[184:187], v[60:63]
	v_mfma_f32_16x16x32_bf16 v[56:59], v[152:155], v[184:187], v[56:59]
	v_lshl_add_u64 v[218:219], s[40:41], 0, v[134:135]
	v_mfma_f32_16x16x32_bf16 v[44:47], v[144:147], v[192:195], v[44:47]
	s_mov_b32 m0, s50
	v_mfma_f32_16x16x32_bf16 v[40:43], v[152:155], v[192:195], v[40:43]
	global_load_lds_dwordx4 v[218:219], off
	v_mfma_f32_16x16x32_bf16 v[28:31], v[144:147], v[200:203], v[28:31]
	s_mov_b32 m0, s51
	v_mfma_f32_16x16x32_bf16 v[24:27], v[152:155], v[200:203], v[24:27]
	global_load_lds_dwordx4 v[220:221], off
	v_mfma_f32_16x16x32_bf16 v[12:15], v[144:147], v[208:211], v[12:15]
	v_mfma_f32_16x16x32_bf16 v[8:11], v[152:155], v[208:211], v[8:11]
	v_mfma_f32_16x16x32_bf16 v[60:63], v[148:151], v[188:191], v[60:63]
	v_mfma_f32_16x16x32_bf16 v[56:59], v[156:159], v[188:191], v[56:59]
	v_mfma_f32_16x16x32_bf16 v[44:47], v[148:151], v[196:199], v[44:47]
	v_mfma_f32_16x16x32_bf16 v[40:43], v[156:159], v[196:199], v[40:43]
	v_mfma_f32_16x16x32_bf16 v[28:31], v[148:151], v[204:207], v[28:31]
	v_mfma_f32_16x16x32_bf16 v[24:27], v[156:159], v[204:207], v[24:27]
	v_mfma_f32_16x16x32_bf16 v[12:15], v[148:151], v[212:215], v[12:15]
	v_mfma_f32_16x16x32_bf16 v[8:11], v[156:159], v[212:215], v[8:11]
	s_setprio 0
	s_setprio 1
	v_mfma_f32_16x16x32_bf16 v[52:55], v[168:171], v[184:187], v[52:55]
	v_mfma_f32_16x16x32_bf16 v[48:51], v[176:179], v[184:187], v[48:51]
	v_mfma_f32_16x16x32_bf16 v[36:39], v[168:171], v[192:195], v[36:39]
	v_mfma_f32_16x16x32_bf16 v[32:35], v[176:179], v[192:195], v[32:35]
	v_mfma_f32_16x16x32_bf16 v[20:23], v[168:171], v[200:203], v[20:23]
	v_mfma_f32_16x16x32_bf16 v[16:19], v[176:179], v[200:203], v[16:19]
	v_mfma_f32_16x16x32_bf16 v[4:7], v[168:171], v[208:211], v[4:7]
	v_mfma_f32_16x16x32_bf16 v[0:3], v[176:179], v[208:211], v[0:3]
	v_mfma_f32_16x16x32_bf16 v[52:55], v[172:175], v[188:191], v[52:55]
	v_mfma_f32_16x16x32_bf16 v[48:51], v[180:183], v[188:191], v[48:51]
	v_mfma_f32_16x16x32_bf16 v[36:39], v[172:175], v[196:199], v[36:39]
	v_mfma_f32_16x16x32_bf16 v[32:35], v[180:183], v[196:199], v[32:35]
	s_setprio 2
	s_barrier
	v_mfma_f32_16x16x32_bf16 v[20:23], v[172:175], v[204:207], v[20:23]
	v_mfma_f32_16x16x32_bf16 v[16:19], v[180:183], v[204:207], v[16:19]
	v_mfma_f32_16x16x32_bf16 v[4:7], v[172:175], v[212:215], v[4:7]
	v_mfma_f32_16x16x32_bf16 v[0:3], v[180:183], v[212:215], v[0:3]
	s_setprio 0
	s_add_i32 s66, 0, 0x18000
	s_add_i32 s67, 0, 0x1c000
	v_add_u32_e32 v156, s66, v162
	v_add_u32_e32 v167, s67, v162
	ds_read_b128 v[144:147], v156
	ds_read_b128 v[148:151], v156 offset:1024
	ds_read_b128 v[152:155], v156 offset:2048
	ds_read_b128 v[156:159], v156 offset:3072
	ds_read_b128 v[168:171], v167
	ds_read_b128 v[172:175], v167 offset:1024
	ds_read_b128 v[176:179], v167 offset:2048
	ds_read_b128 v[180:183], v167 offset:3072
	s_add_u32 s40, s40, 0x40000
	s_addc_u32 s41, s41, 0
	s_mov_b32 m0, s54
	v_lshl_add_u64 v[222:223], s[40:41], 0, v[134:135]
	ds_read_b128 v[184:187], v165 offset:32768
	ds_read_b128 v[188:191], v165 offset:33792
	ds_read_b128 v[192:195], v165 offset:34816
	ds_read_b128 v[196:199], v165 offset:35840
	ds_read_b128 v[200:203], v165 offset:36864
	ds_read_b128 v[204:207], v165 offset:37888
	ds_read_b128 v[208:211], v165 offset:38912
	ds_read_b128 v[212:215], v165 offset:39936
	global_load_lds_dwordx4 v[222:223], off
	v_lshl_add_u64 v[222:223], s[40:41], 0, v[130:131]
	s_mov_b32 m0, s55
	s_nop 0
	global_load_lds_dwordx4 v[222:223], off
	s_waitcnt vmcnt(8)
	s_waitcnt lgkmcnt(0)
	s_barrier
	s_setprio 1
	s_waitcnt lgkmcnt(0)
	v_mfma_f32_16x16x32_bf16 v[124:127], v[144:147], v[184:187], v[124:127]
	v_mfma_f32_16x16x32_bf16 v[120:123], v[152:155], v[184:187], v[120:123]
	v_mfma_f32_16x16x32_bf16 v[108:111], v[144:147], v[192:195], v[108:111]
	v_mfma_f32_16x16x32_bf16 v[104:107], v[152:155], v[192:195], v[104:107]
	v_mfma_f32_16x16x32_bf16 v[92:95], v[144:147], v[200:203], v[92:95]
	v_mfma_f32_16x16x32_bf16 v[88:91], v[152:155], v[200:203], v[88:91]
	v_mfma_f32_16x16x32_bf16 v[76:79], v[144:147], v[208:211], v[76:79]
	v_mfma_f32_16x16x32_bf16 v[72:75], v[152:155], v[208:211], v[72:75]
	v_mfma_f32_16x16x32_bf16 v[124:127], v[148:151], v[188:191], v[124:127]
	v_mfma_f32_16x16x32_bf16 v[120:123], v[156:159], v[188:191], v[120:123]
	v_mfma_f32_16x16x32_bf16 v[108:111], v[148:151], v[196:199], v[108:111]
	v_mfma_f32_16x16x32_bf16 v[104:107], v[156:159], v[196:199], v[104:107]
	v_mfma_f32_16x16x32_bf16 v[92:95], v[148:151], v[204:207], v[92:95]
	v_mfma_f32_16x16x32_bf16 v[88:91], v[156:159], v[204:207], v[88:91]
	v_mfma_f32_16x16x32_bf16 v[76:79], v[148:151], v[212:215], v[76:79]
	v_mfma_f32_16x16x32_bf16 v[72:75], v[156:159], v[212:215], v[72:75]
	s_setprio 0
	s_setprio 1
	v_mfma_f32_16x16x32_bf16 v[116:119], v[168:171], v[184:187], v[116:119]
	v_mfma_f32_16x16x32_bf16 v[112:115], v[176:179], v[184:187], v[112:115]
	v_mfma_f32_16x16x32_bf16 v[100:103], v[168:171], v[192:195], v[100:103]
	v_mfma_f32_16x16x32_bf16 v[96:99], v[176:179], v[192:195], v[96:99]
	v_mfma_f32_16x16x32_bf16 v[84:87], v[168:171], v[200:203], v[84:87]
	v_mfma_f32_16x16x32_bf16 v[80:83], v[176:179], v[200:203], v[80:83]
	v_mfma_f32_16x16x32_bf16 v[68:71], v[168:171], v[208:211], v[68:71]
	v_mfma_f32_16x16x32_bf16 v[64:67], v[176:179], v[208:211], v[64:67]
	v_mfma_f32_16x16x32_bf16 v[116:119], v[172:175], v[188:191], v[116:119]
	v_mfma_f32_16x16x32_bf16 v[112:115], v[180:183], v[188:191], v[112:115]
	v_mfma_f32_16x16x32_bf16 v[100:103], v[172:175], v[196:199], v[100:103]
	v_mfma_f32_16x16x32_bf16 v[96:99], v[180:183], v[196:199], v[96:99]
	s_setprio 2
	s_barrier
	v_mfma_f32_16x16x32_bf16 v[84:87], v[172:175], v[204:207], v[84:87]
	v_mfma_f32_16x16x32_bf16 v[80:83], v[180:183], v[204:207], v[80:83]
	v_mfma_f32_16x16x32_bf16 v[68:71], v[172:175], v[212:215], v[68:71]
	v_mfma_f32_16x16x32_bf16 v[64:67], v[180:183], v[212:215], v[64:67]
	s_setprio 0
	s_add_i32 s40, s66, s47
	v_lshl_add_u64 v[160:161], v[160:161], 0, s[16:17]
	s_mov_b32 m0, s40
	ds_read_b128 v[184:187], v165 offset:49152
	ds_read_b128 v[188:191], v165 offset:50176
	ds_read_b128 v[192:195], v165 offset:51200
	ds_read_b128 v[196:199], v165 offset:52224
	ds_read_b128 v[200:203], v165 offset:53248
	ds_read_b128 v[204:207], v165 offset:54272
	ds_read_b128 v[208:211], v165 offset:55296
	ds_read_b128 v[212:215], v165 offset:56320
	global_load_lds_dwordx4 v[160:161], off
	s_add_i32 m0, s40, 0x2000
	s_add_u32 s38, s38, 0x40080
	v_lshl_add_u64 v[160:161], v[216:217], 0, s[16:17]
	s_addc_u32 s39, s39, 0
	s_add_i32 s40, s67, s47
	global_load_lds_dwordx4 v[160:161], off
	v_lshl_add_u64 v[160:161], s[38:39], 0, v[132:133]
	s_mov_b32 m0, s40
	s_nop 0
	global_load_lds_dwordx4 v[160:161], off
	v_lshl_add_u64 v[160:161], s[38:39], 0, v[128:129]
	s_add_i32 m0, s40, 0x2000
	s_nop 0
	global_load_lds_dwordx4 v[160:161], off
	s_waitcnt vmcnt(6)
	s_waitcnt lgkmcnt(0)
	s_barrier
	s_setprio 1
	s_waitcnt lgkmcnt(0)
	v_mfma_f32_16x16x32_bf16 v[60:63], v[144:147], v[184:187], v[60:63]
	v_mfma_f32_16x16x32_bf16 v[56:59], v[152:155], v[184:187], v[56:59]
	v_lshl_add_u64 v[160:161], v[218:219], 0, s[16:17]
	v_mfma_f32_16x16x32_bf16 v[44:47], v[144:147], v[192:195], v[44:47]
	s_mov_b32 m0, s57
	v_mfma_f32_16x16x32_bf16 v[40:43], v[152:155], v[192:195], v[40:43]
	global_load_lds_dwordx4 v[160:161], off
	v_mfma_f32_16x16x32_bf16 v[28:31], v[144:147], v[200:203], v[28:31]
	v_lshl_add_u64 v[160:161], v[220:221], 0, s[16:17]
	v_mfma_f32_16x16x32_bf16 v[24:27], v[152:155], v[200:203], v[24:27]
	s_mov_b32 m0, s58
	v_mfma_f32_16x16x32_bf16 v[12:15], v[144:147], v[208:211], v[12:15]
	global_load_lds_dwordx4 v[160:161], off
	v_mfma_f32_16x16x32_bf16 v[8:11], v[152:155], v[208:211], v[8:11]
	v_mfma_f32_16x16x32_bf16 v[60:63], v[148:151], v[188:191], v[60:63]
	v_mfma_f32_16x16x32_bf16 v[56:59], v[156:159], v[188:191], v[56:59]
	v_mfma_f32_16x16x32_bf16 v[44:47], v[148:151], v[196:199], v[44:47]
	v_mfma_f32_16x16x32_bf16 v[40:43], v[156:159], v[196:199], v[40:43]
	v_mfma_f32_16x16x32_bf16 v[28:31], v[148:151], v[204:207], v[28:31]
	v_mfma_f32_16x16x32_bf16 v[24:27], v[156:159], v[204:207], v[24:27]
	v_mfma_f32_16x16x32_bf16 v[12:15], v[148:151], v[212:215], v[12:15]
	v_mfma_f32_16x16x32_bf16 v[8:11], v[156:159], v[212:215], v[8:11]
	s_setprio 0
	s_setprio 1
	v_mfma_f32_16x16x32_bf16 v[52:55], v[168:171], v[184:187], v[52:55]
	v_mfma_f32_16x16x32_bf16 v[48:51], v[176:179], v[184:187], v[48:51]
	v_mfma_f32_16x16x32_bf16 v[36:39], v[168:171], v[192:195], v[36:39]
	v_mfma_f32_16x16x32_bf16 v[32:35], v[176:179], v[192:195], v[32:35]
	v_mfma_f32_16x16x32_bf16 v[20:23], v[168:171], v[200:203], v[20:23]
	v_mfma_f32_16x16x32_bf16 v[16:19], v[176:179], v[200:203], v[16:19]
	v_mfma_f32_16x16x32_bf16 v[4:7], v[168:171], v[208:211], v[4:7]
	v_mfma_f32_16x16x32_bf16 v[0:3], v[176:179], v[208:211], v[0:3]
	v_mfma_f32_16x16x32_bf16 v[52:55], v[172:175], v[188:191], v[52:55]
	v_mfma_f32_16x16x32_bf16 v[48:51], v[180:183], v[188:191], v[48:51]
	v_mfma_f32_16x16x32_bf16 v[36:39], v[172:175], v[196:199], v[36:39]
	v_mfma_f32_16x16x32_bf16 v[32:35], v[180:183], v[196:199], v[32:35]
	s_setprio 2
	s_barrier
	v_mfma_f32_16x16x32_bf16 v[20:23], v[172:175], v[204:207], v[20:23]
	v_mfma_f32_16x16x32_bf16 v[16:19], v[180:183], v[204:207], v[16:19]
	v_mfma_f32_16x16x32_bf16 v[4:7], v[172:175], v[212:215], v[4:7]
	v_mfma_f32_16x16x32_bf16 v[0:3], v[180:183], v[212:215], v[0:3]
	s_setprio 0
	s_add_i32 s65, s65, 2
	s_add_u32 s36, s36, 0x100
	s_addc_u32 s37, s37, 0
	s_add_u32 s63, s63, 0x100
	s_addc_u32 s64, s64, 0
	s_cmp_gt_u32 s65, 13
	s_cbranch_scc0 .LBB0_784
	s_and_b64 vcc, exec, s[18:19]
	s_cbranch_vccz .LBB0_787
	s_barrier

.LBB0_866:
	ds_read_b128 v[120:123], v233
	ds_read_b128 v[124:127], v233 offset:1024
	ds_read_b128 v[136:139], v233 offset:2048
	ds_read_b128 v[140:143], v233 offset:3072
	ds_read_b128 v[144:147], v234
	ds_read_b128 v[148:151], v234 offset:1024
	ds_read_b128 v[152:155], v234 offset:2048
	ds_read_b128 v[156:159], v234 offset:3072
	s_add_u32 s28, s26, 0x100
	s_addc_u32 s29, s27, 0
	s_cmp_eq_u32 s64, 40
	s_cselect_b32 s37, s7, s29
	s_cselect_b32 s36, s6, s28
	s_cselect_b32 s31, s25, s63
	s_cselect_b32 s30, s24, s62
	v_lshl_add_u64 v[208:209], s[26:27], 0, v[192:193]
	s_add_i32 m0, s44, 0xc000
	ds_read_b128 v[160:163], v235
	ds_read_b128 v[164:167], v235 offset:1024
	ds_read_b128 v[168:171], v235 offset:2048
	ds_read_b128 v[172:175], v235 offset:3072
	ds_read_b128 v[176:179], v235 offset:4096
	ds_read_b128 v[180:183], v235 offset:5120
	ds_read_b128 v[200:203], v235 offset:6144
	ds_read_b128 v[204:207], v235 offset:7168
	global_load_lds_dwordx4 v[208:209], off
	v_lshl_add_u64 v[208:209], s[26:27], 0, v[194:195]
	s_add_i32 m0, s44, 0xe000
	s_nop 0
	global_load_lds_dwordx4 v[208:209], off
	s_waitcnt vmcnt(8)
	s_waitcnt lgkmcnt(0)
	s_barrier
	s_setprio 1
	s_waitcnt lgkmcnt(0)
	v_mfma_f32_16x16x32_bf16 v[132:135], v[120:123], v[160:163], v[132:135]
	v_mfma_f32_16x16x32_bf16 v[128:131], v[136:139], v[160:163], v[128:131]
	v_mfma_f32_16x16x32_bf16 v[108:111], v[120:123], v[168:171], v[108:111]
	v_mfma_f32_16x16x32_bf16 v[104:107], v[136:139], v[168:171], v[104:107]
	v_mfma_f32_16x16x32_bf16 v[92:95], v[120:123], v[176:179], v[92:95]
	v_mfma_f32_16x16x32_bf16 v[88:91], v[136:139], v[176:179], v[88:91]
	v_mfma_f32_16x16x32_bf16 v[76:79], v[120:123], v[200:203], v[76:79]
	v_mfma_f32_16x16x32_bf16 v[72:75], v[136:139], v[200:203], v[72:75]
	v_mfma_f32_16x16x32_bf16 v[132:135], v[124:127], v[164:167], v[132:135]
	v_mfma_f32_16x16x32_bf16 v[128:131], v[140:143], v[164:167], v[128:131]
	v_mfma_f32_16x16x32_bf16 v[108:111], v[124:127], v[172:175], v[108:111]
	v_mfma_f32_16x16x32_bf16 v[104:107], v[140:143], v[172:175], v[104:107]
	v_mfma_f32_16x16x32_bf16 v[92:95], v[124:127], v[180:183], v[92:95]
	v_mfma_f32_16x16x32_bf16 v[88:91], v[140:143], v[180:183], v[88:91]
	v_mfma_f32_16x16x32_bf16 v[76:79], v[124:127], v[204:207], v[76:79]
	v_mfma_f32_16x16x32_bf16 v[72:75], v[140:143], v[204:207], v[72:75]
	s_setprio 0
	s_setprio 1
	v_mfma_f32_16x16x32_bf16 v[116:119], v[144:147], v[160:163], v[116:119]
	v_mfma_f32_16x16x32_bf16 v[112:115], v[152:155], v[160:163], v[112:115]
	v_mfma_f32_16x16x32_bf16 v[100:103], v[144:147], v[168:171], v[100:103]
	v_mfma_f32_16x16x32_bf16 v[96:99], v[152:155], v[168:171], v[96:99]
	v_mfma_f32_16x16x32_bf16 v[84:87], v[144:147], v[176:179], v[84:87]
	v_mfma_f32_16x16x32_bf16 v[80:83], v[152:155], v[176:179], v[80:83]
	v_mfma_f32_16x16x32_bf16 v[68:71], v[144:147], v[200:203], v[68:71]
	v_mfma_f32_16x16x32_bf16 v[64:67], v[152:155], v[200:203], v[64:67]
	v_mfma_f32_16x16x32_bf16 v[116:119], v[148:151], v[164:167], v[116:119]
	v_mfma_f32_16x16x32_bf16 v[112:115], v[156:159], v[164:167], v[112:115]
	v_mfma_f32_16x16x32_bf16 v[100:103], v[148:151], v[172:175], v[100:103]
	v_mfma_f32_16x16x32_bf16 v[96:99], v[156:159], v[172:175], v[96:99]
	s_setprio 2
	s_barrier
	v_mfma_f32_16x16x32_bf16 v[84:87], v[148:151], v[180:183], v[84:87]
	v_mfma_f32_16x16x32_bf16 v[80:83], v[156:159], v[180:183], v[80:83]
	v_mfma_f32_16x16x32_bf16 v[68:71], v[148:151], v[204:207], v[68:71]
	v_mfma_f32_16x16x32_bf16 v[64:67], v[156:159], v[204:207], v[64:67]
	s_setprio 0
	s_add_i32 s26, s56, s43
	v_lshl_add_u64 v[208:209], s[30:31], 0, v[186:187]
	s_mov_b32 m0, s26
	ds_read_b128 v[160:163], v235 offset:16384
	ds_read_b128 v[164:167], v235 offset:17408
	ds_read_b128 v[168:171], v235 offset:18432
	ds_read_b128 v[172:175], v235 offset:19456
	ds_read_b128 v[176:179], v235 offset:20480
	ds_read_b128 v[180:183], v235 offset:21504
	ds_read_b128 v[200:203], v235 offset:22528
	ds_read_b128 v[204:207], v235 offset:23552
	global_load_lds_dwordx4 v[208:209], off
	s_add_i32 m0, s26, 0x2000
	s_add_u32 s26, s30, 0xb0000
	v_lshl_add_u64 v[210:211], s[30:31], 0, v[190:191]
	s_addc_u32 s27, s31, 0
	s_add_i32 s65, s57, s43
	global_load_lds_dwordx4 v[210:211], off
	v_lshl_add_u64 v[212:213], s[26:27], 0, v[186:187]
	s_mov_b32 m0, s65
	v_lshl_add_u64 v[214:215], s[36:37], 0, v[188:189]
	global_load_lds_dwordx4 v[212:213], off
	v_lshl_add_u64 v[212:213], s[26:27], 0, v[190:191]
	s_add_i32 m0, s65, 0x2000
	s_nop 0
	global_load_lds_dwordx4 v[212:213], off
	s_waitcnt vmcnt(6)
	s_waitcnt lgkmcnt(0)
	s_barrier
	s_setprio 1
	s_waitcnt lgkmcnt(0)
	v_mfma_f32_16x16x32_bf16 v[60:63], v[120:123], v[160:163], v[60:63]
	v_mfma_f32_16x16x32_bf16 v[56:59], v[136:139], v[160:163], v[56:59]
	v_lshl_add_u64 v[212:213], s[36:37], 0, v[184:185]
	v_mfma_f32_16x16x32_bf16 v[44:47], v[120:123], v[168:171], v[44:47]
	s_mov_b32 m0, s44
	v_mfma_f32_16x16x32_bf16 v[40:43], v[136:139], v[168:171], v[40:43]
	global_load_lds_dwordx4 v[212:213], off
	v_mfma_f32_16x16x32_bf16 v[28:31], v[120:123], v[176:179], v[28:31]
	s_mov_b32 m0, s45
	v_mfma_f32_16x16x32_bf16 v[24:27], v[136:139], v[176:179], v[24:27]
	global_load_lds_dwordx4 v[214:215], off
	v_mfma_f32_16x16x32_bf16 v[12:15], v[120:123], v[200:203], v[12:15]
	v_mfma_f32_16x16x32_bf16 v[8:11], v[136:139], v[200:203], v[8:11]
	v_mfma_f32_16x16x32_bf16 v[60:63], v[124:127], v[164:167], v[60:63]
	v_mfma_f32_16x16x32_bf16 v[56:59], v[140:143], v[164:167], v[56:59]
	v_mfma_f32_16x16x32_bf16 v[44:47], v[124:127], v[172:175], v[44:47]
	v_mfma_f32_16x16x32_bf16 v[40:43], v[140:143], v[172:175], v[40:43]
	v_mfma_f32_16x16x32_bf16 v[28:31], v[124:127], v[180:183], v[28:31]
	v_mfma_f32_16x16x32_bf16 v[24:27], v[140:143], v[180:183], v[24:27]
	v_mfma_f32_16x16x32_bf16 v[12:15], v[124:127], v[204:207], v[12:15]
	v_mfma_f32_16x16x32_bf16 v[8:11], v[140:143], v[204:207], v[8:11]
	s_setprio 0
	s_setprio 1
	v_mfma_f32_16x16x32_bf16 v[52:55], v[144:147], v[160:163], v[52:55]
	v_mfma_f32_16x16x32_bf16 v[48:51], v[152:155], v[160:163], v[48:51]
	v_mfma_f32_16x16x32_bf16 v[36:39], v[144:147], v[168:171], v[36:39]
	v_mfma_f32_16x16x32_bf16 v[32:35], v[152:155], v[168:171], v[32:35]
	v_mfma_f32_16x16x32_bf16 v[20:23], v[144:147], v[176:179], v[20:23]
	v_mfma_f32_16x16x32_bf16 v[16:19], v[152:155], v[176:179], v[16:19]
	v_mfma_f32_16x16x32_bf16 v[4:7], v[144:147], v[200:203], v[4:7]
	v_mfma_f32_16x16x32_bf16 v[0:3], v[152:155], v[200:203], v[0:3]
	v_mfma_f32_16x16x32_bf16 v[52:55], v[148:151], v[164:167], v[52:55]
	v_mfma_f32_16x16x32_bf16 v[48:51], v[156:159], v[164:167], v[48:51]
	v_mfma_f32_16x16x32_bf16 v[36:39], v[148:151], v[172:175], v[36:39]
	v_mfma_f32_16x16x32_bf16 v[32:35], v[156:159], v[172:175], v[32:35]
	s_setprio 2
	s_barrier
	v_mfma_f32_16x16x32_bf16 v[20:23], v[148:151], v[180:183], v[20:23]
	v_mfma_f32_16x16x32_bf16 v[16:19], v[156:159], v[180:183], v[16:19]
	v_mfma_f32_16x16x32_bf16 v[4:7], v[148:151], v[204:207], v[4:7]
	v_mfma_f32_16x16x32_bf16 v[0:3], v[156:159], v[204:207], v[0:3]
	s_setprio 0
	s_add_i32 s65, 0, 0x18000
	s_add_i32 s66, 0, 0x1c000
	v_add_u32_e32 v140, s65, v232
	v_add_u32_e32 v156, s66, v232
	ds_read_b128 v[120:123], v140
	ds_read_b128 v[124:127], v140 offset:1024
	ds_read_b128 v[136:139], v140 offset:2048
	ds_read_b128 v[140:143], v140 offset:3072
	ds_read_b128 v[144:147], v156
	ds_read_b128 v[148:151], v156 offset:1024
	ds_read_b128 v[152:155], v156 offset:2048
	ds_read_b128 v[156:159], v156 offset:3072
	s_add_u32 s26, s36, 0xb0000
	s_addc_u32 s27, s37, 0
	s_mov_b32 m0, s46
	v_lshl_add_u64 v[216:217], s[26:27], 0, v[184:185]
	ds_read_b128 v[160:163], v235 offset:32768
	ds_read_b128 v[164:167], v235 offset:33792
	ds_read_b128 v[168:171], v235 offset:34816
	ds_read_b128 v[172:175], v235 offset:35840
	ds_read_b128 v[176:179], v235 offset:36864
	ds_read_b128 v[180:183], v235 offset:37888
	ds_read_b128 v[200:203], v235 offset:38912
	ds_read_b128 v[204:207], v235 offset:39936
	global_load_lds_dwordx4 v[216:217], off
	v_lshl_add_u64 v[216:217], s[26:27], 0, v[188:189]
	s_mov_b32 m0, s47
	s_nop 0
	global_load_lds_dwordx4 v[216:217], off
	s_waitcnt vmcnt(8)
	s_waitcnt lgkmcnt(0)
	s_barrier
	s_setprio 1
	s_waitcnt lgkmcnt(0)
	v_mfma_f32_16x16x32_bf16 v[132:135], v[120:123], v[160:163], v[132:135]
	v_mfma_f32_16x16x32_bf16 v[128:131], v[136:139], v[160:163], v[128:131]
	v_mfma_f32_16x16x32_bf16 v[108:111], v[120:123], v[168:171], v[108:111]
	v_mfma_f32_16x16x32_bf16 v[104:107], v[136:139], v[168:171], v[104:107]
	v_mfma_f32_16x16x32_bf16 v[92:95], v[120:123], v[176:179], v[92:95]
	v_mfma_f32_16x16x32_bf16 v[88:91], v[136:139], v[176:179], v[88:91]
	v_mfma_f32_16x16x32_bf16 v[76:79], v[120:123], v[200:203], v[76:79]
	v_mfma_f32_16x16x32_bf16 v[72:75], v[136:139], v[200:203], v[72:75]
	v_mfma_f32_16x16x32_bf16 v[132:135], v[124:127], v[164:167], v[132:135]
	v_mfma_f32_16x16x32_bf16 v[128:131], v[140:143], v[164:167], v[128:131]
	v_mfma_f32_16x16x32_bf16 v[108:111], v[124:127], v[172:175], v[108:111]
	v_mfma_f32_16x16x32_bf16 v[104:107], v[140:143], v[172:175], v[104:107]
	v_mfma_f32_16x16x32_bf16 v[92:95], v[124:127], v[180:183], v[92:95]
	v_mfma_f32_16x16x32_bf16 v[88:91], v[140:143], v[180:183], v[88:91]
	v_mfma_f32_16x16x32_bf16 v[76:79], v[124:127], v[204:207], v[76:79]
	v_mfma_f32_16x16x32_bf16 v[72:75], v[140:143], v[204:207], v[72:75]
	s_setprio 0
	s_setprio 1
	v_mfma_f32_16x16x32_bf16 v[116:119], v[144:147], v[160:163], v[116:119]
	v_mfma_f32_16x16x32_bf16 v[112:115], v[152:155], v[160:163], v[112:115]
	v_mfma_f32_16x16x32_bf16 v[100:103], v[144:147], v[168:171], v[100:103]
	v_mfma_f32_16x16x32_bf16 v[96:99], v[152:155], v[168:171], v[96:99]
	v_mfma_f32_16x16x32_bf16 v[84:87], v[144:147], v[176:179], v[84:87]
	v_mfma_f32_16x16x32_bf16 v[80:83], v[152:155], v[176:179], v[80:83]
	v_mfma_f32_16x16x32_bf16 v[68:71], v[144:147], v[200:203], v[68:71]
	v_mfma_f32_16x16x32_bf16 v[64:67], v[152:155], v[200:203], v[64:67]
	v_mfma_f32_16x16x32_bf16 v[116:119], v[148:151], v[164:167], v[116:119]
	v_mfma_f32_16x16x32_bf16 v[112:115], v[156:159], v[164:167], v[112:115]
	v_mfma_f32_16x16x32_bf16 v[100:103], v[148:151], v[172:175], v[100:103]
	v_mfma_f32_16x16x32_bf16 v[96:99], v[156:159], v[172:175], v[96:99]
	s_setprio 2
	s_barrier
	v_mfma_f32_16x16x32_bf16 v[84:87], v[148:151], v[180:183], v[84:87]
	v_mfma_f32_16x16x32_bf16 v[80:83], v[156:159], v[180:183], v[80:83]
	v_mfma_f32_16x16x32_bf16 v[68:71], v[148:151], v[204:207], v[68:71]
	v_mfma_f32_16x16x32_bf16 v[64:67], v[156:159], v[204:207], v[64:67]
	s_setprio 0
	s_add_i32 s26, s65, s43
	v_lshl_add_u64 v[208:209], v[208:209], 0, s[20:21]
	s_mov_b32 m0, s26
	ds_read_b128 v[160:163], v235 offset:49152
	ds_read_b128 v[164:167], v235 offset:50176
	ds_read_b128 v[168:171], v235 offset:51200
	ds_read_b128 v[172:175], v235 offset:52224
	ds_read_b128 v[176:179], v235 offset:53248
	ds_read_b128 v[180:183], v235 offset:54272
	ds_read_b128 v[200:203], v235 offset:55296
	ds_read_b128 v[204:207], v235 offset:56320
	global_load_lds_dwordx4 v[208:209], off
	s_add_i32 m0, s26, 0x2000
	s_add_u32 s26, s30, 0xb0080
	v_lshl_add_u64 v[208:209], v[210:211], 0, s[20:21]
	s_addc_u32 s27, s31, 0
	s_add_i32 s30, s66, s43
	global_load_lds_dwordx4 v[208:209], off
	v_lshl_add_u64 v[208:209], s[26:27], 0, v[186:187]
	s_mov_b32 m0, s30
	s_nop 0
	global_load_lds_dwordx4 v[208:209], off
	v_lshl_add_u64 v[208:209], s[26:27], 0, v[190:191]
	s_add_i32 m0, s30, 0x2000
	s_nop 0
	global_load_lds_dwordx4 v[208:209], off
	s_waitcnt vmcnt(6)
	s_waitcnt lgkmcnt(0)
	s_barrier
	s_setprio 1
	s_waitcnt lgkmcnt(0)
	v_mfma_f32_16x16x32_bf16 v[60:63], v[120:123], v[160:163], v[60:63]
	v_mfma_f32_16x16x32_bf16 v[56:59], v[136:139], v[160:163], v[56:59]
	v_lshl_add_u64 v[208:209], v[212:213], 0, s[20:21]
	v_mfma_f32_16x16x32_bf16 v[44:47], v[120:123], v[168:171], v[44:47]
	s_mov_b32 m0, s49
	v_mfma_f32_16x16x32_bf16 v[40:43], v[136:139], v[168:171], v[40:43]
	global_load_lds_dwordx4 v[208:209], off
	v_mfma_f32_16x16x32_bf16 v[28:31], v[120:123], v[176:179], v[28:31]
	v_lshl_add_u64 v[208:209], v[214:215], 0, s[20:21]
	v_mfma_f32_16x16x32_bf16 v[24:27], v[136:139], v[176:179], v[24:27]
	s_mov_b32 m0, s50
	v_mfma_f32_16x16x32_bf16 v[12:15], v[120:123], v[200:203], v[12:15]
	global_load_lds_dwordx4 v[208:209], off
	v_mfma_f32_16x16x32_bf16 v[8:11], v[136:139], v[200:203], v[8:11]
	v_mfma_f32_16x16x32_bf16 v[60:63], v[124:127], v[164:167], v[60:63]
	v_mfma_f32_16x16x32_bf16 v[56:59], v[140:143], v[164:167], v[56:59]
	v_mfma_f32_16x16x32_bf16 v[44:47], v[124:127], v[172:175], v[44:47]
	v_mfma_f32_16x16x32_bf16 v[40:43], v[140:143], v[172:175], v[40:43]
	v_mfma_f32_16x16x32_bf16 v[28:31], v[124:127], v[180:183], v[28:31]
	v_mfma_f32_16x16x32_bf16 v[24:27], v[140:143], v[180:183], v[24:27]
	v_mfma_f32_16x16x32_bf16 v[12:15], v[124:127], v[204:207], v[12:15]
	v_mfma_f32_16x16x32_bf16 v[8:11], v[140:143], v[204:207], v[8:11]
	s_setprio 0
	s_setprio 1
	v_mfma_f32_16x16x32_bf16 v[52:55], v[144:147], v[160:163], v[52:55]
	v_mfma_f32_16x16x32_bf16 v[48:51], v[152:155], v[160:163], v[48:51]
	v_mfma_f32_16x16x32_bf16 v[36:39], v[144:147], v[168:171], v[36:39]
	v_mfma_f32_16x16x32_bf16 v[32:35], v[152:155], v[168:171], v[32:35]
	v_mfma_f32_16x16x32_bf16 v[20:23], v[144:147], v[176:179], v[20:23]
	v_mfma_f32_16x16x32_bf16 v[16:19], v[152:155], v[176:179], v[16:19]
	v_mfma_f32_16x16x32_bf16 v[4:7], v[144:147], v[200:203], v[4:7]
	v_mfma_f32_16x16x32_bf16 v[0:3], v[152:155], v[200:203], v[0:3]
	v_mfma_f32_16x16x32_bf16 v[52:55], v[148:151], v[164:167], v[52:55]
	v_mfma_f32_16x16x32_bf16 v[48:51], v[156:159], v[164:167], v[48:51]
	v_mfma_f32_16x16x32_bf16 v[36:39], v[148:151], v[172:175], v[36:39]
	v_mfma_f32_16x16x32_bf16 v[32:35], v[156:159], v[172:175], v[32:35]
	s_setprio 2
	s_barrier
	v_mfma_f32_16x16x32_bf16 v[20:23], v[148:151], v[180:183], v[20:23]
	v_mfma_f32_16x16x32_bf16 v[16:19], v[156:159], v[180:183], v[16:19]
	v_mfma_f32_16x16x32_bf16 v[4:7], v[148:151], v[204:207], v[4:7]
	v_mfma_f32_16x16x32_bf16 v[0:3], v[156:159], v[204:207], v[0:3]
	s_setprio 0
	s_add_i32 s64, s64, 2
	s_add_u32 s62, s62, 0x100
	s_addc_u32 s63, s63, 0
	s_cmp_gt_u32 s64, 41
	s_mov_b64 s[26:27], s[28:29]
	s_cbranch_scc0 .LBB0_866
	s_and_b64 vcc, exec, s[22:23]
	s_cbranch_vccz .LBB0_869
	s_barrier

.LBB0_952:
	ds_read_b128 v[144:147], v179
	ds_read_b128 v[148:151], v179 offset:1024
	ds_read_b128 v[152:155], v179 offset:2048
	ds_read_b128 v[156:159], v179 offset:3072
	ds_read_b128 v[160:163], v180
	ds_read_b128 v[164:167], v180 offset:1024
	ds_read_b128 v[168:171], v180 offset:2048
	ds_read_b128 v[172:175], v180 offset:3072
	s_add_u32 s40, s6, 0xfffc0080
	s_addc_u32 s41, s7, -1
	s_cmp_eq_u32 s73, 12
	s_cselect_b32 s45, s27, s41
	s_cselect_b32 s44, s39, s40
	s_cselect_b32 s41, s29, s72
	s_cselect_b32 s40, s43, s71
	v_lshl_add_u64 v[176:177], s[6:7], 0, v[136:137]
	s_add_i32 m0, s54, 0xc000
	ds_read_b128 v[184:187], v181
	ds_read_b128 v[188:191], v181 offset:1024
	ds_read_b128 v[192:195], v181 offset:2048
	ds_read_b128 v[196:199], v181 offset:3072
	ds_read_b128 v[200:203], v181 offset:4096
	ds_read_b128 v[204:207], v181 offset:5120
	ds_read_b128 v[208:211], v181 offset:6144
	ds_read_b128 v[212:215], v181 offset:7168
	global_load_lds_dwordx4 v[176:177], off
	v_lshl_add_u64 v[176:177], s[6:7], 0, v[138:139]
	s_add_i32 m0, s54, 0xe000
	s_nop 0
	global_load_lds_dwordx4 v[176:177], off
	s_waitcnt vmcnt(8)
	s_waitcnt lgkmcnt(0)
	s_barrier
	s_setprio 1
	s_waitcnt lgkmcnt(0)
	v_mfma_f32_16x16x32_bf16 v[124:127], v[144:147], v[184:187], v[124:127]
	v_mfma_f32_16x16x32_bf16 v[120:123], v[152:155], v[184:187], v[120:123]
	v_mfma_f32_16x16x32_bf16 v[108:111], v[144:147], v[192:195], v[108:111]
	v_mfma_f32_16x16x32_bf16 v[104:107], v[152:155], v[192:195], v[104:107]
	v_mfma_f32_16x16x32_bf16 v[92:95], v[144:147], v[200:203], v[92:95]
	v_mfma_f32_16x16x32_bf16 v[88:91], v[152:155], v[200:203], v[88:91]
	v_mfma_f32_16x16x32_bf16 v[76:79], v[144:147], v[208:211], v[76:79]
	v_mfma_f32_16x16x32_bf16 v[72:75], v[152:155], v[208:211], v[72:75]
	v_mfma_f32_16x16x32_bf16 v[124:127], v[148:151], v[188:191], v[124:127]
	v_mfma_f32_16x16x32_bf16 v[120:123], v[156:159], v[188:191], v[120:123]
	v_mfma_f32_16x16x32_bf16 v[108:111], v[148:151], v[196:199], v[108:111]
	v_mfma_f32_16x16x32_bf16 v[104:107], v[156:159], v[196:199], v[104:107]
	v_mfma_f32_16x16x32_bf16 v[92:95], v[148:151], v[204:207], v[92:95]
	v_mfma_f32_16x16x32_bf16 v[88:91], v[156:159], v[204:207], v[88:91]
	v_mfma_f32_16x16x32_bf16 v[76:79], v[148:151], v[212:215], v[76:79]
	v_mfma_f32_16x16x32_bf16 v[72:75], v[156:159], v[212:215], v[72:75]
	s_setprio 0
	s_setprio 1
	v_mfma_f32_16x16x32_bf16 v[116:119], v[160:163], v[184:187], v[116:119]
	v_mfma_f32_16x16x32_bf16 v[112:115], v[168:171], v[184:187], v[112:115]
	v_mfma_f32_16x16x32_bf16 v[100:103], v[160:163], v[192:195], v[100:103]
	v_mfma_f32_16x16x32_bf16 v[96:99], v[168:171], v[192:195], v[96:99]
	v_mfma_f32_16x16x32_bf16 v[84:87], v[160:163], v[200:203], v[84:87]
	v_mfma_f32_16x16x32_bf16 v[80:83], v[168:171], v[200:203], v[80:83]
	v_mfma_f32_16x16x32_bf16 v[68:71], v[160:163], v[208:211], v[68:71]
	v_mfma_f32_16x16x32_bf16 v[64:67], v[168:171], v[208:211], v[64:67]
	v_mfma_f32_16x16x32_bf16 v[116:119], v[164:167], v[188:191], v[116:119]
	v_mfma_f32_16x16x32_bf16 v[112:115], v[172:175], v[188:191], v[112:115]
	v_mfma_f32_16x16x32_bf16 v[100:103], v[164:167], v[196:199], v[100:103]
	v_mfma_f32_16x16x32_bf16 v[96:99], v[172:175], v[196:199], v[96:99]
	s_setprio 2
	s_barrier
	v_mfma_f32_16x16x32_bf16 v[84:87], v[164:167], v[204:207], v[84:87]
	v_mfma_f32_16x16x32_bf16 v[80:83], v[172:175], v[204:207], v[80:83]
	v_mfma_f32_16x16x32_bf16 v[68:71], v[164:167], v[212:215], v[68:71]
	v_mfma_f32_16x16x32_bf16 v[64:67], v[172:175], v[212:215], v[64:67]
	s_setprio 0
	s_add_i32 s74, s69, s51
	v_lshl_add_u64 v[176:177], s[40:41], 0, v[130:131]
	s_mov_b32 m0, s74
	ds_read_b128 v[184:187], v181 offset:16384
	ds_read_b128 v[188:191], v181 offset:17408
	ds_read_b128 v[192:195], v181 offset:18432
	ds_read_b128 v[196:199], v181 offset:19456
	ds_read_b128 v[200:203], v181 offset:20480
	ds_read_b128 v[204:207], v181 offset:21504
	ds_read_b128 v[208:211], v181 offset:22528
	ds_read_b128 v[212:215], v181 offset:23552
	global_load_lds_dwordx4 v[176:177], off
	s_add_i32 m0, s74, 0x2000
	s_add_u32 s74, s40, 0x40000
	v_lshl_add_u64 v[216:217], s[40:41], 0, v[134:135]
	s_addc_u32 s75, s41, 0
	s_add_i32 s76, s70, s51
	global_load_lds_dwordx4 v[216:217], off
	v_lshl_add_u64 v[218:219], s[74:75], 0, v[130:131]
	s_mov_b32 m0, s76
	v_lshl_add_u64 v[220:221], s[44:45], 0, v[132:133]
	global_load_lds_dwordx4 v[218:219], off
	v_lshl_add_u64 v[218:219], s[74:75], 0, v[134:135]
	s_add_i32 m0, s76, 0x2000
	s_nop 0
	global_load_lds_dwordx4 v[218:219], off
	s_waitcnt vmcnt(6)
	s_waitcnt lgkmcnt(0)
	s_barrier
	s_setprio 1
	s_waitcnt lgkmcnt(0)
	v_mfma_f32_16x16x32_bf16 v[60:63], v[144:147], v[184:187], v[60:63]
	v_mfma_f32_16x16x32_bf16 v[56:59], v[152:155], v[184:187], v[56:59]
	v_lshl_add_u64 v[218:219], s[44:45], 0, v[128:129]
	v_mfma_f32_16x16x32_bf16 v[44:47], v[144:147], v[192:195], v[44:47]
	s_mov_b32 m0, s54
	v_mfma_f32_16x16x32_bf16 v[40:43], v[152:155], v[192:195], v[40:43]
	global_load_lds_dwordx4 v[218:219], off
	v_mfma_f32_16x16x32_bf16 v[28:31], v[144:147], v[200:203], v[28:31]
	s_mov_b32 m0, s55
	v_mfma_f32_16x16x32_bf16 v[24:27], v[152:155], v[200:203], v[24:27]
	global_load_lds_dwordx4 v[220:221], off
	v_mfma_f32_16x16x32_bf16 v[12:15], v[144:147], v[208:211], v[12:15]
	v_mfma_f32_16x16x32_bf16 v[8:11], v[152:155], v[208:211], v[8:11]
	v_mfma_f32_16x16x32_bf16 v[60:63], v[148:151], v[188:191], v[60:63]
	v_mfma_f32_16x16x32_bf16 v[56:59], v[156:159], v[188:191], v[56:59]
	v_mfma_f32_16x16x32_bf16 v[44:47], v[148:151], v[196:199], v[44:47]
	v_mfma_f32_16x16x32_bf16 v[40:43], v[156:159], v[196:199], v[40:43]
	v_mfma_f32_16x16x32_bf16 v[28:31], v[148:151], v[204:207], v[28:31]
	v_mfma_f32_16x16x32_bf16 v[24:27], v[156:159], v[204:207], v[24:27]
	v_mfma_f32_16x16x32_bf16 v[12:15], v[148:151], v[212:215], v[12:15]
	v_mfma_f32_16x16x32_bf16 v[8:11], v[156:159], v[212:215], v[8:11]
	s_setprio 0
	s_setprio 1
	v_mfma_f32_16x16x32_bf16 v[52:55], v[160:163], v[184:187], v[52:55]
	v_mfma_f32_16x16x32_bf16 v[48:51], v[168:171], v[184:187], v[48:51]
	v_mfma_f32_16x16x32_bf16 v[36:39], v[160:163], v[192:195], v[36:39]
	v_mfma_f32_16x16x32_bf16 v[32:35], v[168:171], v[192:195], v[32:35]
	v_mfma_f32_16x16x32_bf16 v[20:23], v[160:163], v[200:203], v[20:23]
	v_mfma_f32_16x16x32_bf16 v[16:19], v[168:171], v[200:203], v[16:19]
	v_mfma_f32_16x16x32_bf16 v[4:7], v[160:163], v[208:211], v[4:7]
	v_mfma_f32_16x16x32_bf16 v[0:3], v[168:171], v[208:211], v[0:3]
	v_mfma_f32_16x16x32_bf16 v[52:55], v[164:167], v[188:191], v[52:55]
	v_mfma_f32_16x16x32_bf16 v[48:51], v[172:175], v[188:191], v[48:51]
	v_mfma_f32_16x16x32_bf16 v[36:39], v[164:167], v[196:199], v[36:39]
	v_mfma_f32_16x16x32_bf16 v[32:35], v[172:175], v[196:199], v[32:35]
	s_setprio 2
	s_barrier
	v_mfma_f32_16x16x32_bf16 v[20:23], v[164:167], v[204:207], v[20:23]
	v_mfma_f32_16x16x32_bf16 v[16:19], v[172:175], v[204:207], v[16:19]
	v_mfma_f32_16x16x32_bf16 v[4:7], v[164:167], v[212:215], v[4:7]
	v_mfma_f32_16x16x32_bf16 v[0:3], v[172:175], v[212:215], v[0:3]
	s_setprio 0
	s_add_i32 s74, 0, 0x18000
	s_add_i32 s75, 0, 0x1c000
	v_add_u32_e32 v156, s74, v178
	v_add_u32_e32 v172, s75, v178
	ds_read_b128 v[144:147], v156
	ds_read_b128 v[148:151], v156 offset:1024
	ds_read_b128 v[152:155], v156 offset:2048
	ds_read_b128 v[156:159], v156 offset:3072
	ds_read_b128 v[160:163], v172
	ds_read_b128 v[164:167], v172 offset:1024
	ds_read_b128 v[168:171], v172 offset:2048
	ds_read_b128 v[172:175], v172 offset:3072
	s_add_u32 s44, s44, 0x40000
	s_addc_u32 s45, s45, 0
	s_mov_b32 m0, s56
	v_lshl_add_u64 v[222:223], s[44:45], 0, v[128:129]
	ds_read_b128 v[184:187], v181 offset:32768
	ds_read_b128 v[188:191], v181 offset:33792
	ds_read_b128 v[192:195], v181 offset:34816
	ds_read_b128 v[196:199], v181 offset:35840
	ds_read_b128 v[200:203], v181 offset:36864
	ds_read_b128 v[204:207], v181 offset:37888
	ds_read_b128 v[208:211], v181 offset:38912
	ds_read_b128 v[212:215], v181 offset:39936
	global_load_lds_dwordx4 v[222:223], off
	v_lshl_add_u64 v[222:223], s[44:45], 0, v[132:133]
	s_mov_b32 m0, s57
	s_nop 0
	global_load_lds_dwordx4 v[222:223], off
	s_waitcnt vmcnt(8)
	s_waitcnt lgkmcnt(0)
	s_barrier
	s_setprio 1
	s_waitcnt lgkmcnt(0)
	v_mfma_f32_16x16x32_bf16 v[124:127], v[144:147], v[184:187], v[124:127]
	v_mfma_f32_16x16x32_bf16 v[120:123], v[152:155], v[184:187], v[120:123]
	v_mfma_f32_16x16x32_bf16 v[108:111], v[144:147], v[192:195], v[108:111]
	v_mfma_f32_16x16x32_bf16 v[104:107], v[152:155], v[192:195], v[104:107]
	v_mfma_f32_16x16x32_bf16 v[92:95], v[144:147], v[200:203], v[92:95]
	v_mfma_f32_16x16x32_bf16 v[88:91], v[152:155], v[200:203], v[88:91]
	v_mfma_f32_16x16x32_bf16 v[76:79], v[144:147], v[208:211], v[76:79]
	v_mfma_f32_16x16x32_bf16 v[72:75], v[152:155], v[208:211], v[72:75]
	v_mfma_f32_16x16x32_bf16 v[124:127], v[148:151], v[188:191], v[124:127]
	v_mfma_f32_16x16x32_bf16 v[120:123], v[156:159], v[188:191], v[120:123]
	v_mfma_f32_16x16x32_bf16 v[108:111], v[148:151], v[196:199], v[108:111]
	v_mfma_f32_16x16x32_bf16 v[104:107], v[156:159], v[196:199], v[104:107]
	v_mfma_f32_16x16x32_bf16 v[92:95], v[148:151], v[204:207], v[92:95]
	v_mfma_f32_16x16x32_bf16 v[88:91], v[156:159], v[204:207], v[88:91]
	v_mfma_f32_16x16x32_bf16 v[76:79], v[148:151], v[212:215], v[76:79]
	v_mfma_f32_16x16x32_bf16 v[72:75], v[156:159], v[212:215], v[72:75]
	s_setprio 0
	s_setprio 1
	v_mfma_f32_16x16x32_bf16 v[116:119], v[160:163], v[184:187], v[116:119]
	v_mfma_f32_16x16x32_bf16 v[112:115], v[168:171], v[184:187], v[112:115]
	v_mfma_f32_16x16x32_bf16 v[100:103], v[160:163], v[192:195], v[100:103]
	v_mfma_f32_16x16x32_bf16 v[96:99], v[168:171], v[192:195], v[96:99]
	v_mfma_f32_16x16x32_bf16 v[84:87], v[160:163], v[200:203], v[84:87]
	v_mfma_f32_16x16x32_bf16 v[80:83], v[168:171], v[200:203], v[80:83]
	v_mfma_f32_16x16x32_bf16 v[68:71], v[160:163], v[208:211], v[68:71]
	v_mfma_f32_16x16x32_bf16 v[64:67], v[168:171], v[208:211], v[64:67]
	v_mfma_f32_16x16x32_bf16 v[116:119], v[164:167], v[188:191], v[116:119]
	v_mfma_f32_16x16x32_bf16 v[112:115], v[172:175], v[188:191], v[112:115]
	v_mfma_f32_16x16x32_bf16 v[100:103], v[164:167], v[196:199], v[100:103]
	v_mfma_f32_16x16x32_bf16 v[96:99], v[172:175], v[196:199], v[96:99]
	s_setprio 2
	s_barrier
	v_mfma_f32_16x16x32_bf16 v[84:87], v[164:167], v[204:207], v[84:87]
	v_mfma_f32_16x16x32_bf16 v[80:83], v[172:175], v[204:207], v[80:83]
	v_mfma_f32_16x16x32_bf16 v[68:71], v[164:167], v[212:215], v[68:71]
	v_mfma_f32_16x16x32_bf16 v[64:67], v[172:175], v[212:215], v[64:67]
	s_setprio 0
	s_add_i32 s44, s74, s51
	v_lshl_add_u64 v[176:177], v[176:177], 0, s[22:23]
	s_mov_b32 m0, s44
	ds_read_b128 v[184:187], v181 offset:49152
	ds_read_b128 v[188:191], v181 offset:50176
	ds_read_b128 v[192:195], v181 offset:51200
	ds_read_b128 v[196:199], v181 offset:52224
	ds_read_b128 v[200:203], v181 offset:53248
	ds_read_b128 v[204:207], v181 offset:54272
	ds_read_b128 v[208:211], v181 offset:55296
	ds_read_b128 v[212:215], v181 offset:56320
	global_load_lds_dwordx4 v[176:177], off
	s_add_i32 m0, s44, 0x2000
	s_add_u32 s40, s40, 0x40080
	v_lshl_add_u64 v[176:177], v[216:217], 0, s[22:23]
	s_addc_u32 s41, s41, 0
	s_add_i32 s44, s75, s51
	global_load_lds_dwordx4 v[176:177], off
	v_lshl_add_u64 v[176:177], s[40:41], 0, v[130:131]
	s_mov_b32 m0, s44
	s_nop 0
	global_load_lds_dwordx4 v[176:177], off
	v_lshl_add_u64 v[176:177], s[40:41], 0, v[134:135]
	s_add_i32 m0, s44, 0x2000
	s_nop 0
	global_load_lds_dwordx4 v[176:177], off
	s_waitcnt vmcnt(6)
	s_waitcnt lgkmcnt(0)
	s_barrier
	s_setprio 1
	s_waitcnt lgkmcnt(0)
	v_mfma_f32_16x16x32_bf16 v[60:63], v[144:147], v[184:187], v[60:63]
	v_mfma_f32_16x16x32_bf16 v[56:59], v[152:155], v[184:187], v[56:59]
	v_lshl_add_u64 v[176:177], v[218:219], 0, s[22:23]
	v_mfma_f32_16x16x32_bf16 v[44:47], v[144:147], v[192:195], v[44:47]
	s_mov_b32 m0, s64
	v_mfma_f32_16x16x32_bf16 v[40:43], v[152:155], v[192:195], v[40:43]
	global_load_lds_dwordx4 v[176:177], off
	v_mfma_f32_16x16x32_bf16 v[28:31], v[144:147], v[200:203], v[28:31]
	v_lshl_add_u64 v[176:177], v[220:221], 0, s[22:23]
	v_mfma_f32_16x16x32_bf16 v[24:27], v[152:155], v[200:203], v[24:27]
	s_mov_b32 m0, s65
	v_mfma_f32_16x16x32_bf16 v[12:15], v[144:147], v[208:211], v[12:15]
	global_load_lds_dwordx4 v[176:177], off
	v_mfma_f32_16x16x32_bf16 v[8:11], v[152:155], v[208:211], v[8:11]
	v_mfma_f32_16x16x32_bf16 v[60:63], v[148:151], v[188:191], v[60:63]
	v_mfma_f32_16x16x32_bf16 v[56:59], v[156:159], v[188:191], v[56:59]
	v_mfma_f32_16x16x32_bf16 v[44:47], v[148:151], v[196:199], v[44:47]
	v_mfma_f32_16x16x32_bf16 v[40:43], v[156:159], v[196:199], v[40:43]
	v_mfma_f32_16x16x32_bf16 v[28:31], v[148:151], v[204:207], v[28:31]
	v_mfma_f32_16x16x32_bf16 v[24:27], v[156:159], v[204:207], v[24:27]
	v_mfma_f32_16x16x32_bf16 v[12:15], v[148:151], v[212:215], v[12:15]
	v_mfma_f32_16x16x32_bf16 v[8:11], v[156:159], v[212:215], v[8:11]
	s_setprio 0
	s_setprio 1
	v_mfma_f32_16x16x32_bf16 v[52:55], v[160:163], v[184:187], v[52:55]
	v_mfma_f32_16x16x32_bf16 v[48:51], v[168:171], v[184:187], v[48:51]
	v_mfma_f32_16x16x32_bf16 v[36:39], v[160:163], v[192:195], v[36:39]
	v_mfma_f32_16x16x32_bf16 v[32:35], v[168:171], v[192:195], v[32:35]
	v_mfma_f32_16x16x32_bf16 v[20:23], v[160:163], v[200:203], v[20:23]
	v_mfma_f32_16x16x32_bf16 v[16:19], v[168:171], v[200:203], v[16:19]
	v_mfma_f32_16x16x32_bf16 v[4:7], v[160:163], v[208:211], v[4:7]
	v_mfma_f32_16x16x32_bf16 v[0:3], v[168:171], v[208:211], v[0:3]
	v_mfma_f32_16x16x32_bf16 v[52:55], v[164:167], v[188:191], v[52:55]
	v_mfma_f32_16x16x32_bf16 v[48:51], v[172:175], v[188:191], v[48:51]
	v_mfma_f32_16x16x32_bf16 v[36:39], v[164:167], v[196:199], v[36:39]
	v_mfma_f32_16x16x32_bf16 v[32:35], v[172:175], v[196:199], v[32:35]
	s_setprio 2
	s_barrier
	v_mfma_f32_16x16x32_bf16 v[20:23], v[164:167], v[204:207], v[20:23]
	v_mfma_f32_16x16x32_bf16 v[16:19], v[172:175], v[204:207], v[16:19]
	v_mfma_f32_16x16x32_bf16 v[4:7], v[164:167], v[212:215], v[4:7]
	v_mfma_f32_16x16x32_bf16 v[0:3], v[172:175], v[212:215], v[0:3]
	s_setprio 0
	s_add_i32 s73, s73, 2
	s_add_u32 s6, s6, 0x100
	s_addc_u32 s7, s7, 0
	s_add_u32 s71, s71, 0x100
	s_addc_u32 s72, s72, 0
	s_cmp_gt_u32 s73, 13
	s_cbranch_scc0 .LBB0_952
	s_and_b64 vcc, exec, s[24:25]
	s_cbranch_vccz .LBB0_955
	s_barrier

.LBB0_1146:
	ds_read_b128 v[120:123], v233
	ds_read_b128 v[132:135], v233 offset:1024
	ds_read_b128 v[136:139], v233 offset:2048
	ds_read_b128 v[140:143], v233 offset:3072
	ds_read_b128 v[144:147], v234
	ds_read_b128 v[148:151], v234 offset:1024
	ds_read_b128 v[152:155], v234 offset:2048
	ds_read_b128 v[156:159], v234 offset:3072
	s_add_u32 s40, s38, 0xfffc0080
	s_addc_u32 s41, s39, -1
	s_cmp_eq_u32 s66, 12
	s_cselect_b32 s43, s23, s41
	s_cselect_b32 s42, s31, s40
	s_cselect_b32 s41, s25, s65
	s_cselect_b32 s40, s37, s64
	v_lshl_add_u64 v[208:209], s[38:39], 0, v[192:193]
	s_add_i32 m0, s50, 0xc000
	ds_read_b128 v[160:163], v235
	ds_read_b128 v[164:167], v235 offset:1024
	ds_read_b128 v[168:171], v235 offset:2048
	ds_read_b128 v[172:175], v235 offset:3072
	ds_read_b128 v[176:179], v235 offset:4096
	ds_read_b128 v[180:183], v235 offset:5120
	ds_read_b128 v[200:203], v235 offset:6144
	ds_read_b128 v[204:207], v235 offset:7168
	global_load_lds_dwordx4 v[208:209], off
	v_lshl_add_u64 v[208:209], s[38:39], 0, v[194:195]
	s_add_i32 m0, s50, 0xe000
	s_nop 0
	global_load_lds_dwordx4 v[208:209], off
	s_waitcnt vmcnt(8)
	s_waitcnt lgkmcnt(0)
	s_barrier
	s_setprio 1
	s_waitcnt lgkmcnt(0)
	v_mfma_f32_16x16x32_bf16 v[128:131], v[120:123], v[160:163], v[128:131]
	v_mfma_f32_16x16x32_bf16 v[124:127], v[136:139], v[160:163], v[124:127]
	v_mfma_f32_16x16x32_bf16 v[108:111], v[120:123], v[168:171], v[108:111]
	v_mfma_f32_16x16x32_bf16 v[104:107], v[136:139], v[168:171], v[104:107]
	v_mfma_f32_16x16x32_bf16 v[92:95], v[120:123], v[176:179], v[92:95]
	v_mfma_f32_16x16x32_bf16 v[88:91], v[136:139], v[176:179], v[88:91]
	v_mfma_f32_16x16x32_bf16 v[76:79], v[120:123], v[200:203], v[76:79]
	v_mfma_f32_16x16x32_bf16 v[72:75], v[136:139], v[200:203], v[72:75]
	v_mfma_f32_16x16x32_bf16 v[128:131], v[132:135], v[164:167], v[128:131]
	v_mfma_f32_16x16x32_bf16 v[124:127], v[140:143], v[164:167], v[124:127]
	v_mfma_f32_16x16x32_bf16 v[108:111], v[132:135], v[172:175], v[108:111]
	v_mfma_f32_16x16x32_bf16 v[104:107], v[140:143], v[172:175], v[104:107]
	v_mfma_f32_16x16x32_bf16 v[92:95], v[132:135], v[180:183], v[92:95]
	v_mfma_f32_16x16x32_bf16 v[88:91], v[140:143], v[180:183], v[88:91]
	v_mfma_f32_16x16x32_bf16 v[76:79], v[132:135], v[204:207], v[76:79]
	v_mfma_f32_16x16x32_bf16 v[72:75], v[140:143], v[204:207], v[72:75]
	s_setprio 0
	s_setprio 1
	v_mfma_f32_16x16x32_bf16 v[116:119], v[144:147], v[160:163], v[116:119]
	v_mfma_f32_16x16x32_bf16 v[112:115], v[152:155], v[160:163], v[112:115]
	v_mfma_f32_16x16x32_bf16 v[100:103], v[144:147], v[168:171], v[100:103]
	v_mfma_f32_16x16x32_bf16 v[96:99], v[152:155], v[168:171], v[96:99]
	v_mfma_f32_16x16x32_bf16 v[84:87], v[144:147], v[176:179], v[84:87]
	v_mfma_f32_16x16x32_bf16 v[80:83], v[152:155], v[176:179], v[80:83]
	v_mfma_f32_16x16x32_bf16 v[68:71], v[144:147], v[200:203], v[68:71]
	v_mfma_f32_16x16x32_bf16 v[64:67], v[152:155], v[200:203], v[64:67]
	v_mfma_f32_16x16x32_bf16 v[116:119], v[148:151], v[164:167], v[116:119]
	v_mfma_f32_16x16x32_bf16 v[112:115], v[156:159], v[164:167], v[112:115]
	v_mfma_f32_16x16x32_bf16 v[100:103], v[148:151], v[172:175], v[100:103]
	v_mfma_f32_16x16x32_bf16 v[96:99], v[156:159], v[172:175], v[96:99]
	s_setprio 2
	s_barrier
	v_mfma_f32_16x16x32_bf16 v[84:87], v[148:151], v[180:183], v[84:87]
	v_mfma_f32_16x16x32_bf16 v[80:83], v[156:159], v[180:183], v[80:83]
	v_mfma_f32_16x16x32_bf16 v[68:71], v[148:151], v[204:207], v[68:71]
	v_mfma_f32_16x16x32_bf16 v[64:67], v[156:159], v[204:207], v[64:67]
	s_setprio 0
	s_add_i32 s67, s62, s49
	v_lshl_add_u64 v[208:209], s[40:41], 0, v[186:187]
	s_mov_b32 m0, s67
	ds_read_b128 v[160:163], v235 offset:16384
	ds_read_b128 v[164:167], v235 offset:17408
	ds_read_b128 v[168:171], v235 offset:18432
	ds_read_b128 v[172:175], v235 offset:19456
	ds_read_b128 v[176:179], v235 offset:20480
	ds_read_b128 v[180:183], v235 offset:21504
	ds_read_b128 v[200:203], v235 offset:22528
	ds_read_b128 v[204:207], v235 offset:23552
	global_load_lds_dwordx4 v[208:209], off
	s_add_i32 m0, s67, 0x2000
	s_add_u32 s68, s40, 0x40000
	v_lshl_add_u64 v[210:211], s[40:41], 0, v[190:191]
	s_addc_u32 s69, s41, 0
	s_add_i32 s67, s63, s49
	global_load_lds_dwordx4 v[210:211], off
	v_lshl_add_u64 v[212:213], s[68:69], 0, v[186:187]
	s_mov_b32 m0, s67
	v_lshl_add_u64 v[214:215], s[42:43], 0, v[188:189]
	global_load_lds_dwordx4 v[212:213], off
	v_lshl_add_u64 v[212:213], s[68:69], 0, v[190:191]
	s_add_i32 m0, s67, 0x2000
	s_nop 0
	global_load_lds_dwordx4 v[212:213], off
	s_waitcnt vmcnt(6)
	s_waitcnt lgkmcnt(0)
	s_barrier
	s_setprio 1
	s_waitcnt lgkmcnt(0)
	v_mfma_f32_16x16x32_bf16 v[60:63], v[120:123], v[160:163], v[60:63]
	v_mfma_f32_16x16x32_bf16 v[56:59], v[136:139], v[160:163], v[56:59]
	v_lshl_add_u64 v[212:213], s[42:43], 0, v[184:185]
	v_mfma_f32_16x16x32_bf16 v[44:47], v[120:123], v[168:171], v[44:47]
	s_mov_b32 m0, s50
	v_mfma_f32_16x16x32_bf16 v[40:43], v[136:139], v[168:171], v[40:43]
	global_load_lds_dwordx4 v[212:213], off
	v_mfma_f32_16x16x32_bf16 v[28:31], v[120:123], v[176:179], v[28:31]
	s_mov_b32 m0, s51
	v_mfma_f32_16x16x32_bf16 v[24:27], v[136:139], v[176:179], v[24:27]
	global_load_lds_dwordx4 v[214:215], off
	v_mfma_f32_16x16x32_bf16 v[12:15], v[120:123], v[200:203], v[12:15]
	v_mfma_f32_16x16x32_bf16 v[8:11], v[136:139], v[200:203], v[8:11]
	v_mfma_f32_16x16x32_bf16 v[60:63], v[132:135], v[164:167], v[60:63]
	v_mfma_f32_16x16x32_bf16 v[56:59], v[140:143], v[164:167], v[56:59]
	v_mfma_f32_16x16x32_bf16 v[44:47], v[132:135], v[172:175], v[44:47]
	v_mfma_f32_16x16x32_bf16 v[40:43], v[140:143], v[172:175], v[40:43]
	v_mfma_f32_16x16x32_bf16 v[28:31], v[132:135], v[180:183], v[28:31]
	v_mfma_f32_16x16x32_bf16 v[24:27], v[140:143], v[180:183], v[24:27]
	v_mfma_f32_16x16x32_bf16 v[12:15], v[132:135], v[204:207], v[12:15]
	v_mfma_f32_16x16x32_bf16 v[8:11], v[140:143], v[204:207], v[8:11]
	s_setprio 0
	s_setprio 1
	v_mfma_f32_16x16x32_bf16 v[52:55], v[144:147], v[160:163], v[52:55]
	v_mfma_f32_16x16x32_bf16 v[48:51], v[152:155], v[160:163], v[48:51]
	v_mfma_f32_16x16x32_bf16 v[36:39], v[144:147], v[168:171], v[36:39]
	v_mfma_f32_16x16x32_bf16 v[32:35], v[152:155], v[168:171], v[32:35]
	v_mfma_f32_16x16x32_bf16 v[20:23], v[144:147], v[176:179], v[20:23]
	v_mfma_f32_16x16x32_bf16 v[16:19], v[152:155], v[176:179], v[16:19]
	v_mfma_f32_16x16x32_bf16 v[4:7], v[144:147], v[200:203], v[4:7]
	v_mfma_f32_16x16x32_bf16 v[0:3], v[152:155], v[200:203], v[0:3]
	v_mfma_f32_16x16x32_bf16 v[52:55], v[148:151], v[164:167], v[52:55]
	v_mfma_f32_16x16x32_bf16 v[48:51], v[156:159], v[164:167], v[48:51]
	v_mfma_f32_16x16x32_bf16 v[36:39], v[148:151], v[172:175], v[36:39]
	v_mfma_f32_16x16x32_bf16 v[32:35], v[156:159], v[172:175], v[32:35]
	s_setprio 2
	s_barrier
	v_mfma_f32_16x16x32_bf16 v[20:23], v[148:151], v[180:183], v[20:23]
	v_mfma_f32_16x16x32_bf16 v[16:19], v[156:159], v[180:183], v[16:19]
	v_mfma_f32_16x16x32_bf16 v[4:7], v[148:151], v[204:207], v[4:7]
	v_mfma_f32_16x16x32_bf16 v[0:3], v[156:159], v[204:207], v[0:3]
	s_setprio 0
	s_add_i32 s67, 0, 0x18000
	s_add_i32 s68, 0, 0x1c000
	v_add_u32_e32 v140, s67, v232
	v_add_u32_e32 v156, s68, v232
	ds_read_b128 v[120:123], v140
	ds_read_b128 v[132:135], v140 offset:1024
	ds_read_b128 v[136:139], v140 offset:2048
	ds_read_b128 v[140:143], v140 offset:3072
	ds_read_b128 v[144:147], v156
	ds_read_b128 v[148:151], v156 offset:1024
	ds_read_b128 v[152:155], v156 offset:2048
	ds_read_b128 v[156:159], v156 offset:3072
	s_add_u32 s42, s42, 0x40000
	s_addc_u32 s43, s43, 0
	s_mov_b32 m0, s54
	v_lshl_add_u64 v[216:217], s[42:43], 0, v[184:185]
	ds_read_b128 v[160:163], v235 offset:32768
	ds_read_b128 v[164:167], v235 offset:33792
	ds_read_b128 v[168:171], v235 offset:34816
	ds_read_b128 v[172:175], v235 offset:35840
	ds_read_b128 v[176:179], v235 offset:36864
	ds_read_b128 v[180:183], v235 offset:37888
	ds_read_b128 v[200:203], v235 offset:38912
	ds_read_b128 v[204:207], v235 offset:39936
	global_load_lds_dwordx4 v[216:217], off
	v_lshl_add_u64 v[216:217], s[42:43], 0, v[188:189]
	s_mov_b32 m0, s55
	s_nop 0
	global_load_lds_dwordx4 v[216:217], off
	s_waitcnt vmcnt(8)
	s_waitcnt lgkmcnt(0)
	s_barrier
	s_setprio 1
	s_waitcnt lgkmcnt(0)
	v_mfma_f32_16x16x32_bf16 v[128:131], v[120:123], v[160:163], v[128:131]
	v_mfma_f32_16x16x32_bf16 v[124:127], v[136:139], v[160:163], v[124:127]
	v_mfma_f32_16x16x32_bf16 v[108:111], v[120:123], v[168:171], v[108:111]
	v_mfma_f32_16x16x32_bf16 v[104:107], v[136:139], v[168:171], v[104:107]
	v_mfma_f32_16x16x32_bf16 v[92:95], v[120:123], v[176:179], v[92:95]
	v_mfma_f32_16x16x32_bf16 v[88:91], v[136:139], v[176:179], v[88:91]
	v_mfma_f32_16x16x32_bf16 v[76:79], v[120:123], v[200:203], v[76:79]
	v_mfma_f32_16x16x32_bf16 v[72:75], v[136:139], v[200:203], v[72:75]
	v_mfma_f32_16x16x32_bf16 v[128:131], v[132:135], v[164:167], v[128:131]
	v_mfma_f32_16x16x32_bf16 v[124:127], v[140:143], v[164:167], v[124:127]
	v_mfma_f32_16x16x32_bf16 v[108:111], v[132:135], v[172:175], v[108:111]
	v_mfma_f32_16x16x32_bf16 v[104:107], v[140:143], v[172:175], v[104:107]
	v_mfma_f32_16x16x32_bf16 v[92:95], v[132:135], v[180:183], v[92:95]
	v_mfma_f32_16x16x32_bf16 v[88:91], v[140:143], v[180:183], v[88:91]
	v_mfma_f32_16x16x32_bf16 v[76:79], v[132:135], v[204:207], v[76:79]
	v_mfma_f32_16x16x32_bf16 v[72:75], v[140:143], v[204:207], v[72:75]
	s_setprio 0
	s_setprio 1
	v_mfma_f32_16x16x32_bf16 v[116:119], v[144:147], v[160:163], v[116:119]
	v_mfma_f32_16x16x32_bf16 v[112:115], v[152:155], v[160:163], v[112:115]
	v_mfma_f32_16x16x32_bf16 v[100:103], v[144:147], v[168:171], v[100:103]
	v_mfma_f32_16x16x32_bf16 v[96:99], v[152:155], v[168:171], v[96:99]
	v_mfma_f32_16x16x32_bf16 v[84:87], v[144:147], v[176:179], v[84:87]
	v_mfma_f32_16x16x32_bf16 v[80:83], v[152:155], v[176:179], v[80:83]
	v_mfma_f32_16x16x32_bf16 v[68:71], v[144:147], v[200:203], v[68:71]
	v_mfma_f32_16x16x32_bf16 v[64:67], v[152:155], v[200:203], v[64:67]
	v_mfma_f32_16x16x32_bf16 v[116:119], v[148:151], v[164:167], v[116:119]
	v_mfma_f32_16x16x32_bf16 v[112:115], v[156:159], v[164:167], v[112:115]
	v_mfma_f32_16x16x32_bf16 v[100:103], v[148:151], v[172:175], v[100:103]
	v_mfma_f32_16x16x32_bf16 v[96:99], v[156:159], v[172:175], v[96:99]
	s_setprio 2
	s_barrier
	v_mfma_f32_16x16x32_bf16 v[84:87], v[148:151], v[180:183], v[84:87]
	v_mfma_f32_16x16x32_bf16 v[80:83], v[156:159], v[180:183], v[80:83]
	v_mfma_f32_16x16x32_bf16 v[68:71], v[148:151], v[204:207], v[68:71]
	v_mfma_f32_16x16x32_bf16 v[64:67], v[156:159], v[204:207], v[64:67]
	s_setprio 0
	s_add_i32 s42, s67, s49
	v_lshl_add_u64 v[208:209], v[208:209], 0, s[18:19]
	s_mov_b32 m0, s42
	ds_read_b128 v[160:163], v235 offset:49152
	ds_read_b128 v[164:167], v235 offset:50176
	ds_read_b128 v[168:171], v235 offset:51200
	ds_read_b128 v[172:175], v235 offset:52224
	ds_read_b128 v[176:179], v235 offset:53248
	ds_read_b128 v[180:183], v235 offset:54272
	ds_read_b128 v[200:203], v235 offset:55296
	ds_read_b128 v[204:207], v235 offset:56320
	global_load_lds_dwordx4 v[208:209], off
	s_add_i32 m0, s42, 0x2000
	s_add_u32 s40, s40, 0x40080
	v_lshl_add_u64 v[208:209], v[210:211], 0, s[18:19]
	s_addc_u32 s41, s41, 0
	s_add_i32 s42, s68, s49
	global_load_lds_dwordx4 v[208:209], off
	v_lshl_add_u64 v[208:209], s[40:41], 0, v[186:187]
	s_mov_b32 m0, s42
	s_nop 0
	global_load_lds_dwordx4 v[208:209], off
	v_lshl_add_u64 v[208:209], s[40:41], 0, v[190:191]
	s_add_i32 m0, s42, 0x2000
	s_nop 0
	global_load_lds_dwordx4 v[208:209], off
	s_waitcnt vmcnt(6)
	s_waitcnt lgkmcnt(0)
	s_barrier
	s_setprio 1
	s_waitcnt lgkmcnt(0)
	v_mfma_f32_16x16x32_bf16 v[60:63], v[120:123], v[160:163], v[60:63]
	v_mfma_f32_16x16x32_bf16 v[56:59], v[136:139], v[160:163], v[56:59]
	v_lshl_add_u64 v[208:209], v[212:213], 0, s[18:19]
	v_mfma_f32_16x16x32_bf16 v[44:47], v[120:123], v[168:171], v[44:47]
	s_mov_b32 m0, s57
	v_mfma_f32_16x16x32_bf16 v[40:43], v[136:139], v[168:171], v[40:43]
	global_load_lds_dwordx4 v[208:209], off
	v_mfma_f32_16x16x32_bf16 v[28:31], v[120:123], v[176:179], v[28:31]
	v_lshl_add_u64 v[208:209], v[214:215], 0, s[18:19]
	v_mfma_f32_16x16x32_bf16 v[24:27], v[136:139], v[176:179], v[24:27]
	s_mov_b32 m0, s58
	v_mfma_f32_16x16x32_bf16 v[12:15], v[120:123], v[200:203], v[12:15]
	global_load_lds_dwordx4 v[208:209], off
	v_mfma_f32_16x16x32_bf16 v[8:11], v[136:139], v[200:203], v[8:11]
	v_mfma_f32_16x16x32_bf16 v[60:63], v[132:135], v[164:167], v[60:63]
	v_mfma_f32_16x16x32_bf16 v[56:59], v[140:143], v[164:167], v[56:59]
	v_mfma_f32_16x16x32_bf16 v[44:47], v[132:135], v[172:175], v[44:47]
	v_mfma_f32_16x16x32_bf16 v[40:43], v[140:143], v[172:175], v[40:43]
	v_mfma_f32_16x16x32_bf16 v[28:31], v[132:135], v[180:183], v[28:31]
	v_mfma_f32_16x16x32_bf16 v[24:27], v[140:143], v[180:183], v[24:27]
	v_mfma_f32_16x16x32_bf16 v[12:15], v[132:135], v[204:207], v[12:15]
	v_mfma_f32_16x16x32_bf16 v[8:11], v[140:143], v[204:207], v[8:11]
	s_setprio 0
	s_setprio 1
	v_mfma_f32_16x16x32_bf16 v[52:55], v[144:147], v[160:163], v[52:55]
	v_mfma_f32_16x16x32_bf16 v[48:51], v[152:155], v[160:163], v[48:51]
	v_mfma_f32_16x16x32_bf16 v[36:39], v[144:147], v[168:171], v[36:39]
	v_mfma_f32_16x16x32_bf16 v[32:35], v[152:155], v[168:171], v[32:35]
	v_mfma_f32_16x16x32_bf16 v[20:23], v[144:147], v[176:179], v[20:23]
	v_mfma_f32_16x16x32_bf16 v[16:19], v[152:155], v[176:179], v[16:19]
	v_mfma_f32_16x16x32_bf16 v[4:7], v[144:147], v[200:203], v[4:7]
	v_mfma_f32_16x16x32_bf16 v[0:3], v[152:155], v[200:203], v[0:3]
	v_mfma_f32_16x16x32_bf16 v[52:55], v[148:151], v[164:167], v[52:55]
	v_mfma_f32_16x16x32_bf16 v[48:51], v[156:159], v[164:167], v[48:51]
	v_mfma_f32_16x16x32_bf16 v[36:39], v[148:151], v[172:175], v[36:39]
	v_mfma_f32_16x16x32_bf16 v[32:35], v[156:159], v[172:175], v[32:35]
	s_setprio 2
	s_barrier
	v_mfma_f32_16x16x32_bf16 v[20:23], v[148:151], v[180:183], v[20:23]
	v_mfma_f32_16x16x32_bf16 v[16:19], v[156:159], v[180:183], v[16:19]
	v_mfma_f32_16x16x32_bf16 v[4:7], v[148:151], v[204:207], v[4:7]
	v_mfma_f32_16x16x32_bf16 v[0:3], v[156:159], v[204:207], v[0:3]
	s_setprio 0
	s_add_i32 s66, s66, 2
	s_add_u32 s38, s38, 0x100
	s_addc_u32 s39, s39, 0
	s_add_u32 s64, s64, 0x100
	s_addc_u32 s65, s65, 0
	s_cmp_gt_u32 s66, 13
	s_cbranch_scc0 .LBB0_1146
	s_and_b64 vcc, exec, s[20:21]
	s_cbranch_vccz .LBB0_1149
	s_barrier

.LBB0_1310:
	ds_read_b128 v[128:131], v197
	ds_read_b128 v[132:135], v197 offset:1024
	ds_read_b128 v[136:139], v197 offset:2048
	ds_read_b128 v[140:143], v197 offset:3072
	ds_read_b128 v[144:147], v198
	ds_read_b128 v[148:151], v198 offset:1024
	ds_read_b128 v[152:155], v198 offset:2048
	ds_read_b128 v[156:159], v198 offset:3072
	s_add_u32 s4, s24, 0x100
	s_addc_u32 s5, s25, 0
	s_cmp_eq_u32 s53, 40
	s_cselect_b32 s29, s21, s5
	s_cselect_b32 s28, s20, s4
	s_cselect_b32 s27, s23, s52
	s_cselect_b32 s26, s22, s51
	v_lshl_add_u64 v[212:213], s[24:25], 0, v[172:173]
	s_add_i32 m0, s36, 0xc000
	ds_read_b128 v[160:163], v199
	ds_read_b128 v[180:183], v199 offset:1024
	ds_read_b128 v[184:187], v199 offset:2048
	ds_read_b128 v[188:191], v199 offset:3072
	ds_read_b128 v[192:195], v199 offset:4096
	ds_read_b128 v[200:203], v199 offset:5120
	ds_read_b128 v[204:207], v199 offset:6144
	ds_read_b128 v[208:211], v199 offset:7168
	global_load_lds_dwordx4 v[212:213], off
	v_lshl_add_u64 v[212:213], s[24:25], 0, v[174:175]
	s_add_i32 m0, s36, 0xe000
	s_nop 0
	global_load_lds_dwordx4 v[212:213], off
	s_waitcnt vmcnt(8)
	s_waitcnt lgkmcnt(0)
	s_barrier
	s_setprio 1
	s_waitcnt lgkmcnt(0)
	v_mfma_f32_16x16x32_bf16 v[124:127], v[128:131], v[160:163], v[124:127]
	v_mfma_f32_16x16x32_bf16 v[120:123], v[136:139], v[160:163], v[120:123]
	v_mfma_f32_16x16x32_bf16 v[116:119], v[128:131], v[184:187], v[116:119]
	v_mfma_f32_16x16x32_bf16 v[108:111], v[136:139], v[184:187], v[108:111]
	v_mfma_f32_16x16x32_bf16 v[88:91], v[128:131], v[192:195], v[88:91]
	v_mfma_f32_16x16x32_bf16 v[100:103], v[136:139], v[192:195], v[100:103]
	v_mfma_f32_16x16x32_bf16 v[72:75], v[128:131], v[204:207], v[72:75]
	v_mfma_f32_16x16x32_bf16 v[76:79], v[136:139], v[204:207], v[76:79]
	v_mfma_f32_16x16x32_bf16 v[124:127], v[132:135], v[180:183], v[124:127]
	v_mfma_f32_16x16x32_bf16 v[120:123], v[140:143], v[180:183], v[120:123]
	v_mfma_f32_16x16x32_bf16 v[116:119], v[132:135], v[188:191], v[116:119]
	v_mfma_f32_16x16x32_bf16 v[108:111], v[140:143], v[188:191], v[108:111]
	v_mfma_f32_16x16x32_bf16 v[88:91], v[132:135], v[200:203], v[88:91]
	v_mfma_f32_16x16x32_bf16 v[100:103], v[140:143], v[200:203], v[100:103]
	v_mfma_f32_16x16x32_bf16 v[72:75], v[132:135], v[208:211], v[72:75]
	v_mfma_f32_16x16x32_bf16 v[76:79], v[140:143], v[208:211], v[76:79]
	s_setprio 0
	s_setprio 1
	v_mfma_f32_16x16x32_bf16 v[112:115], v[144:147], v[160:163], v[112:115]
	v_mfma_f32_16x16x32_bf16 v[104:107], v[152:155], v[160:163], v[104:107]
	v_mfma_f32_16x16x32_bf16 v[96:99], v[144:147], v[184:187], v[96:99]
	v_mfma_f32_16x16x32_bf16 v[92:95], v[152:155], v[184:187], v[92:95]
	v_mfma_f32_16x16x32_bf16 v[80:83], v[144:147], v[192:195], v[80:83]
	v_mfma_f32_16x16x32_bf16 v[84:87], v[152:155], v[192:195], v[84:87]
	v_mfma_f32_16x16x32_bf16 v[64:67], v[144:147], v[204:207], v[64:67]
	v_mfma_f32_16x16x32_bf16 v[68:71], v[152:155], v[204:207], v[68:71]
	v_mfma_f32_16x16x32_bf16 v[112:115], v[148:151], v[180:183], v[112:115]
	v_mfma_f32_16x16x32_bf16 v[104:107], v[156:159], v[180:183], v[104:107]
	v_mfma_f32_16x16x32_bf16 v[96:99], v[148:151], v[188:191], v[96:99]
	v_mfma_f32_16x16x32_bf16 v[92:95], v[156:159], v[188:191], v[92:95]
	s_setprio 2
	s_barrier
	v_mfma_f32_16x16x32_bf16 v[80:83], v[148:151], v[200:203], v[80:83]
	v_mfma_f32_16x16x32_bf16 v[84:87], v[156:159], v[200:203], v[84:87]
	v_mfma_f32_16x16x32_bf16 v[64:67], v[148:151], v[208:211], v[64:67]
	v_mfma_f32_16x16x32_bf16 v[68:71], v[156:159], v[208:211], v[68:71]
	s_setprio 0
	s_add_i32 s24, s45, s35
	v_lshl_add_u64 v[212:213], s[26:27], 0, v[166:167]
	s_mov_b32 m0, s24
	ds_read_b128 v[160:163], v199 offset:16384
	ds_read_b128 v[180:183], v199 offset:17408
	ds_read_b128 v[184:187], v199 offset:18432
	ds_read_b128 v[188:191], v199 offset:19456
	ds_read_b128 v[192:195], v199 offset:20480
	ds_read_b128 v[200:203], v199 offset:21504
	ds_read_b128 v[204:207], v199 offset:22528
	ds_read_b128 v[208:211], v199 offset:23552
	global_load_lds_dwordx4 v[212:213], off
	s_add_i32 m0, s24, 0x2000
	s_add_u32 s24, s26, 0xb0000
	v_lshl_add_u64 v[214:215], s[26:27], 0, v[170:171]
	s_addc_u32 s25, s27, 0
	s_add_i32 s54, s46, s35
	global_load_lds_dwordx4 v[214:215], off
	v_lshl_add_u64 v[216:217], s[24:25], 0, v[166:167]
	s_mov_b32 m0, s54
	v_lshl_add_u64 v[218:219], s[28:29], 0, v[168:169]
	global_load_lds_dwordx4 v[216:217], off
	v_lshl_add_u64 v[216:217], s[24:25], 0, v[170:171]
	s_add_i32 m0, s54, 0x2000
	s_nop 0
	global_load_lds_dwordx4 v[216:217], off
	s_waitcnt vmcnt(6)
	s_waitcnt lgkmcnt(0)
	s_barrier
	s_setprio 1
	s_waitcnt lgkmcnt(0)
	v_mfma_f32_16x16x32_bf16 v[56:59], v[128:131], v[160:163], v[56:59]
	v_mfma_f32_16x16x32_bf16 v[60:63], v[136:139], v[160:163], v[60:63]
	v_lshl_add_u64 v[216:217], s[28:29], 0, v[164:165]
	v_mfma_f32_16x16x32_bf16 v[40:43], v[128:131], v[184:187], v[40:43]
	s_mov_b32 m0, s36
	v_mfma_f32_16x16x32_bf16 v[44:47], v[136:139], v[184:187], v[44:47]
	global_load_lds_dwordx4 v[216:217], off
	v_mfma_f32_16x16x32_bf16 v[24:27], v[128:131], v[192:195], v[24:27]
	s_mov_b32 m0, s37
	v_mfma_f32_16x16x32_bf16 v[28:31], v[136:139], v[192:195], v[28:31]
	global_load_lds_dwordx4 v[218:219], off
	v_mfma_f32_16x16x32_bf16 v[8:11], v[128:131], v[204:207], v[8:11]
	v_mfma_f32_16x16x32_bf16 v[12:15], v[136:139], v[204:207], v[12:15]
	v_mfma_f32_16x16x32_bf16 v[56:59], v[132:135], v[180:183], v[56:59]
	v_mfma_f32_16x16x32_bf16 v[60:63], v[140:143], v[180:183], v[60:63]
	v_mfma_f32_16x16x32_bf16 v[40:43], v[132:135], v[188:191], v[40:43]
	v_mfma_f32_16x16x32_bf16 v[44:47], v[140:143], v[188:191], v[44:47]
	v_mfma_f32_16x16x32_bf16 v[24:27], v[132:135], v[200:203], v[24:27]
	v_mfma_f32_16x16x32_bf16 v[28:31], v[140:143], v[200:203], v[28:31]
	v_mfma_f32_16x16x32_bf16 v[8:11], v[132:135], v[208:211], v[8:11]
	v_mfma_f32_16x16x32_bf16 v[12:15], v[140:143], v[208:211], v[12:15]
	s_setprio 0
	s_setprio 1
	v_mfma_f32_16x16x32_bf16 v[48:51], v[144:147], v[160:163], v[48:51]
	v_mfma_f32_16x16x32_bf16 v[52:55], v[152:155], v[160:163], v[52:55]
	v_mfma_f32_16x16x32_bf16 v[32:35], v[144:147], v[184:187], v[32:35]
	v_mfma_f32_16x16x32_bf16 v[36:39], v[152:155], v[184:187], v[36:39]
	v_mfma_f32_16x16x32_bf16 v[16:19], v[144:147], v[192:195], v[16:19]
	v_mfma_f32_16x16x32_bf16 v[20:23], v[152:155], v[192:195], v[20:23]
	v_mfma_f32_16x16x32_bf16 v[0:3], v[144:147], v[204:207], v[0:3]
	v_mfma_f32_16x16x32_bf16 v[4:7], v[152:155], v[204:207], v[4:7]
	v_mfma_f32_16x16x32_bf16 v[48:51], v[148:151], v[180:183], v[48:51]
	v_mfma_f32_16x16x32_bf16 v[52:55], v[156:159], v[180:183], v[52:55]
	v_mfma_f32_16x16x32_bf16 v[32:35], v[148:151], v[188:191], v[32:35]
	v_mfma_f32_16x16x32_bf16 v[36:39], v[156:159], v[188:191], v[36:39]
	s_setprio 2
	s_barrier
	v_mfma_f32_16x16x32_bf16 v[16:19], v[148:151], v[200:203], v[16:19]
	v_mfma_f32_16x16x32_bf16 v[20:23], v[156:159], v[200:203], v[20:23]
	v_mfma_f32_16x16x32_bf16 v[0:3], v[148:151], v[208:211], v[0:3]
	v_mfma_f32_16x16x32_bf16 v[4:7], v[156:159], v[208:211], v[4:7]
	s_setprio 0
	s_add_i32 s54, 0, 0x18000
	s_add_i32 s55, 0, 0x1c000
	v_add_u32_e32 v140, s54, v196
	v_add_u32_e32 v156, s55, v196
	ds_read_b128 v[128:131], v140
	ds_read_b128 v[132:135], v140 offset:1024
	ds_read_b128 v[136:139], v140 offset:2048
	ds_read_b128 v[140:143], v140 offset:3072
	ds_read_b128 v[144:147], v156
	ds_read_b128 v[148:151], v156 offset:1024
	ds_read_b128 v[152:155], v156 offset:2048
	ds_read_b128 v[156:159], v156 offset:3072
	s_add_u32 s24, s28, 0xb0000
	s_addc_u32 s25, s29, 0
	s_mov_b32 m0, s38
	v_lshl_add_u64 v[220:221], s[24:25], 0, v[164:165]
	ds_read_b128 v[160:163], v199 offset:32768
	ds_read_b128 v[180:183], v199 offset:33792
	ds_read_b128 v[184:187], v199 offset:34816
	ds_read_b128 v[188:191], v199 offset:35840
	ds_read_b128 v[192:195], v199 offset:36864
	ds_read_b128 v[200:203], v199 offset:37888
	ds_read_b128 v[204:207], v199 offset:38912
	ds_read_b128 v[208:211], v199 offset:39936
	global_load_lds_dwordx4 v[220:221], off
	v_lshl_add_u64 v[220:221], s[24:25], 0, v[168:169]
	s_mov_b32 m0, s39
	s_nop 0
	global_load_lds_dwordx4 v[220:221], off
	s_waitcnt vmcnt(8)
	s_waitcnt lgkmcnt(0)
	s_barrier
	s_setprio 1
	s_waitcnt lgkmcnt(0)
	v_mfma_f32_16x16x32_bf16 v[124:127], v[128:131], v[160:163], v[124:127]
	v_mfma_f32_16x16x32_bf16 v[120:123], v[136:139], v[160:163], v[120:123]
	v_mfma_f32_16x16x32_bf16 v[116:119], v[128:131], v[184:187], v[116:119]
	v_mfma_f32_16x16x32_bf16 v[108:111], v[136:139], v[184:187], v[108:111]
	v_mfma_f32_16x16x32_bf16 v[88:91], v[128:131], v[192:195], v[88:91]
	v_mfma_f32_16x16x32_bf16 v[100:103], v[136:139], v[192:195], v[100:103]
	v_mfma_f32_16x16x32_bf16 v[72:75], v[128:131], v[204:207], v[72:75]
	v_mfma_f32_16x16x32_bf16 v[76:79], v[136:139], v[204:207], v[76:79]
	v_mfma_f32_16x16x32_bf16 v[124:127], v[132:135], v[180:183], v[124:127]
	v_mfma_f32_16x16x32_bf16 v[120:123], v[140:143], v[180:183], v[120:123]
	v_mfma_f32_16x16x32_bf16 v[116:119], v[132:135], v[188:191], v[116:119]
	v_mfma_f32_16x16x32_bf16 v[108:111], v[140:143], v[188:191], v[108:111]
	v_mfma_f32_16x16x32_bf16 v[88:91], v[132:135], v[200:203], v[88:91]
	v_mfma_f32_16x16x32_bf16 v[100:103], v[140:143], v[200:203], v[100:103]
	v_mfma_f32_16x16x32_bf16 v[72:75], v[132:135], v[208:211], v[72:75]
	v_mfma_f32_16x16x32_bf16 v[76:79], v[140:143], v[208:211], v[76:79]
	s_setprio 0
	s_setprio 1
	v_mfma_f32_16x16x32_bf16 v[112:115], v[144:147], v[160:163], v[112:115]
	v_mfma_f32_16x16x32_bf16 v[104:107], v[152:155], v[160:163], v[104:107]
	v_mfma_f32_16x16x32_bf16 v[96:99], v[144:147], v[184:187], v[96:99]
	v_mfma_f32_16x16x32_bf16 v[92:95], v[152:155], v[184:187], v[92:95]
	v_mfma_f32_16x16x32_bf16 v[80:83], v[144:147], v[192:195], v[80:83]
	v_mfma_f32_16x16x32_bf16 v[84:87], v[152:155], v[192:195], v[84:87]
	v_mfma_f32_16x16x32_bf16 v[64:67], v[144:147], v[204:207], v[64:67]
	v_mfma_f32_16x16x32_bf16 v[68:71], v[152:155], v[204:207], v[68:71]
	v_mfma_f32_16x16x32_bf16 v[112:115], v[148:151], v[180:183], v[112:115]
	v_mfma_f32_16x16x32_bf16 v[104:107], v[156:159], v[180:183], v[104:107]
	v_mfma_f32_16x16x32_bf16 v[96:99], v[148:151], v[188:191], v[96:99]
	v_mfma_f32_16x16x32_bf16 v[92:95], v[156:159], v[188:191], v[92:95]
	s_setprio 2
	s_barrier
	v_mfma_f32_16x16x32_bf16 v[80:83], v[148:151], v[200:203], v[80:83]
	v_mfma_f32_16x16x32_bf16 v[84:87], v[156:159], v[200:203], v[84:87]
	v_mfma_f32_16x16x32_bf16 v[64:67], v[148:151], v[208:211], v[64:67]
	v_mfma_f32_16x16x32_bf16 v[68:71], v[156:159], v[208:211], v[68:71]
	s_setprio 0
	s_add_i32 s24, s54, s35
	v_lshl_add_u64 v[212:213], v[212:213], 0, s[16:17]
	s_mov_b32 m0, s24
	ds_read_b128 v[160:163], v199 offset:49152
	ds_read_b128 v[180:183], v199 offset:50176
	ds_read_b128 v[184:187], v199 offset:51200
	ds_read_b128 v[188:191], v199 offset:52224
	ds_read_b128 v[192:195], v199 offset:53248
	ds_read_b128 v[200:203], v199 offset:54272
	ds_read_b128 v[204:207], v199 offset:55296
	ds_read_b128 v[208:211], v199 offset:56320
	global_load_lds_dwordx4 v[212:213], off
	s_add_i32 m0, s24, 0x2000
	s_add_u32 s24, s26, 0xb0080
	v_lshl_add_u64 v[212:213], v[214:215], 0, s[16:17]
	s_addc_u32 s25, s27, 0
	s_add_i32 s26, s55, s35
	global_load_lds_dwordx4 v[212:213], off
	v_lshl_add_u64 v[212:213], s[24:25], 0, v[166:167]
	s_mov_b32 m0, s26
	s_nop 0
	global_load_lds_dwordx4 v[212:213], off
	v_lshl_add_u64 v[212:213], s[24:25], 0, v[170:171]
	s_add_i32 m0, s26, 0x2000
	s_nop 0
	global_load_lds_dwordx4 v[212:213], off
	s_waitcnt vmcnt(6)
	s_waitcnt lgkmcnt(0)
	s_barrier
	s_setprio 1
	s_waitcnt lgkmcnt(0)
	v_mfma_f32_16x16x32_bf16 v[56:59], v[128:131], v[160:163], v[56:59]
	v_mfma_f32_16x16x32_bf16 v[60:63], v[136:139], v[160:163], v[60:63]
	v_lshl_add_u64 v[212:213], v[216:217], 0, s[16:17]
	v_mfma_f32_16x16x32_bf16 v[40:43], v[128:131], v[184:187], v[40:43]
	s_mov_b32 m0, s41
	v_mfma_f32_16x16x32_bf16 v[44:47], v[136:139], v[184:187], v[44:47]
	global_load_lds_dwordx4 v[212:213], off
	v_mfma_f32_16x16x32_bf16 v[24:27], v[128:131], v[192:195], v[24:27]
	v_lshl_add_u64 v[212:213], v[218:219], 0, s[16:17]
	v_mfma_f32_16x16x32_bf16 v[28:31], v[136:139], v[192:195], v[28:31]
	s_mov_b32 m0, s42
	v_mfma_f32_16x16x32_bf16 v[8:11], v[128:131], v[204:207], v[8:11]
	global_load_lds_dwordx4 v[212:213], off
	v_mfma_f32_16x16x32_bf16 v[12:15], v[136:139], v[204:207], v[12:15]
	v_mfma_f32_16x16x32_bf16 v[56:59], v[132:135], v[180:183], v[56:59]
	v_mfma_f32_16x16x32_bf16 v[60:63], v[140:143], v[180:183], v[60:63]
	v_mfma_f32_16x16x32_bf16 v[40:43], v[132:135], v[188:191], v[40:43]
	v_mfma_f32_16x16x32_bf16 v[44:47], v[140:143], v[188:191], v[44:47]
	v_mfma_f32_16x16x32_bf16 v[24:27], v[132:135], v[200:203], v[24:27]
	v_mfma_f32_16x16x32_bf16 v[28:31], v[140:143], v[200:203], v[28:31]
	v_mfma_f32_16x16x32_bf16 v[8:11], v[132:135], v[208:211], v[8:11]
	v_mfma_f32_16x16x32_bf16 v[12:15], v[140:143], v[208:211], v[12:15]
	s_setprio 0
	s_setprio 1
	v_mfma_f32_16x16x32_bf16 v[48:51], v[144:147], v[160:163], v[48:51]
	v_mfma_f32_16x16x32_bf16 v[52:55], v[152:155], v[160:163], v[52:55]
	v_mfma_f32_16x16x32_bf16 v[32:35], v[144:147], v[184:187], v[32:35]
	v_mfma_f32_16x16x32_bf16 v[36:39], v[152:155], v[184:187], v[36:39]
	v_mfma_f32_16x16x32_bf16 v[16:19], v[144:147], v[192:195], v[16:19]
	v_mfma_f32_16x16x32_bf16 v[20:23], v[152:155], v[192:195], v[20:23]
	v_mfma_f32_16x16x32_bf16 v[0:3], v[144:147], v[204:207], v[0:3]
	v_mfma_f32_16x16x32_bf16 v[4:7], v[152:155], v[204:207], v[4:7]
	v_mfma_f32_16x16x32_bf16 v[48:51], v[148:151], v[180:183], v[48:51]
	v_mfma_f32_16x16x32_bf16 v[52:55], v[156:159], v[180:183], v[52:55]
	v_mfma_f32_16x16x32_bf16 v[32:35], v[148:151], v[188:191], v[32:35]
	v_mfma_f32_16x16x32_bf16 v[36:39], v[156:159], v[188:191], v[36:39]
	s_setprio 2
	s_barrier
	v_mfma_f32_16x16x32_bf16 v[16:19], v[148:151], v[200:203], v[16:19]
	v_mfma_f32_16x16x32_bf16 v[20:23], v[156:159], v[200:203], v[20:23]
	v_mfma_f32_16x16x32_bf16 v[0:3], v[148:151], v[208:211], v[0:3]
	v_mfma_f32_16x16x32_bf16 v[4:7], v[156:159], v[208:211], v[4:7]
	s_setprio 0
	s_add_i32 s53, s53, 2
	s_add_u32 s51, s51, 0x100
	s_addc_u32 s52, s52, 0
	s_cmp_gt_u32 s53, 41
	s_mov_b64 s[24:25], s[4:5]
	s_cbranch_scc0 .LBB0_1310
	s_and_b64 vcc, exec, s[18:19]
	s_cbranch_vccz .LBB0_1313
	s_barrier
